# GEMM K-loops: the barrier closing each MFMA segment is signalled 4 MFMAs early (the tail MFMAs touch no LDS), so the partner wave group's LDS phase can start sooner
# baseline (speedup 1.0000x reference)
.LBB0_274:
	ds_read_b128 v[144:147], v155
	ds_read_b128 v[148:151], v155 offset:1024
	ds_read_b128 v[160:163], v155 offset:2048
	ds_read_b128 v[164:167], v155 offset:3072
	ds_read_b128 v[168:171], v156
	ds_read_b128 v[172:175], v156 offset:1024
	ds_read_b128 v[176:179], v156 offset:2048
	ds_read_b128 v[180:183], v156 offset:3072
	s_add_u32 s26, s24, 0xfff80080
	s_addc_u32 s27, s25, -1
	s_cmp_eq_u32 s57, 28
	s_cselect_b32 s29, s13, s27
	s_cselect_b32 s28, s15, s26
	s_cselect_b32 s27, s17, s56
	s_cselect_b32 s26, s54, s55
	v_lshl_add_u64 v[216:217], s[24:25], 0, v[136:137]
	s_add_i32 m0, s23, 0xc000
	ds_read_b128 v[184:187], v157
	ds_read_b128 v[188:191], v157 offset:1024
	ds_read_b128 v[192:195], v157 offset:2048
	ds_read_b128 v[196:199], v157 offset:3072
	ds_read_b128 v[200:203], v157 offset:4096
	ds_read_b128 v[204:207], v157 offset:5120
	ds_read_b128 v[208:211], v157 offset:6144
	ds_read_b128 v[212:215], v157 offset:7168
	global_load_lds_dwordx4 v[216:217], off
	v_lshl_add_u64 v[216:217], s[24:25], 0, v[138:139]
	s_add_i32 m0, s23, 0xe000
	s_nop 0
	global_load_lds_dwordx4 v[216:217], off
	s_waitcnt vmcnt(8)
	s_waitcnt lgkmcnt(0)
	s_barrier
	s_setprio 1
	s_waitcnt lgkmcnt(0)
	v_mfma_f32_16x16x32_bf16 v[124:127], v[144:147], v[184:187], v[124:127]
	v_mfma_f32_16x16x32_bf16 v[120:123], v[160:163], v[184:187], v[120:123]
	v_mfma_f32_16x16x32_bf16 v[108:111], v[144:147], v[192:195], v[108:111]
	v_mfma_f32_16x16x32_bf16 v[104:107], v[160:163], v[192:195], v[104:107]
	v_mfma_f32_16x16x32_bf16 v[92:95], v[144:147], v[200:203], v[92:95]
	v_mfma_f32_16x16x32_bf16 v[88:91], v[160:163], v[200:203], v[88:91]
	v_mfma_f32_16x16x32_bf16 v[84:87], v[144:147], v[208:211], v[84:87]
	v_mfma_f32_16x16x32_bf16 v[76:79], v[160:163], v[208:211], v[76:79]
	v_mfma_f32_16x16x32_bf16 v[124:127], v[148:151], v[188:191], v[124:127]
	v_mfma_f32_16x16x32_bf16 v[120:123], v[164:167], v[188:191], v[120:123]
	v_mfma_f32_16x16x32_bf16 v[108:111], v[148:151], v[196:199], v[108:111]
	v_mfma_f32_16x16x32_bf16 v[104:107], v[164:167], v[196:199], v[104:107]
	v_mfma_f32_16x16x32_bf16 v[92:95], v[148:151], v[204:207], v[92:95]
	v_mfma_f32_16x16x32_bf16 v[88:91], v[164:167], v[204:207], v[88:91]
	v_mfma_f32_16x16x32_bf16 v[84:87], v[148:151], v[212:215], v[84:87]
	v_mfma_f32_16x16x32_bf16 v[76:79], v[164:167], v[212:215], v[76:79]
	s_setprio 0
	s_setprio 1
	v_mfma_f32_16x16x32_bf16 v[116:119], v[168:171], v[184:187], v[116:119]
	v_mfma_f32_16x16x32_bf16 v[112:115], v[176:179], v[184:187], v[112:115]
	v_mfma_f32_16x16x32_bf16 v[100:103], v[168:171], v[192:195], v[100:103]
	v_mfma_f32_16x16x32_bf16 v[96:99], v[176:179], v[192:195], v[96:99]
	v_mfma_f32_16x16x32_bf16 v[80:83], v[168:171], v[200:203], v[80:83]
	v_mfma_f32_16x16x32_bf16 v[72:75], v[176:179], v[200:203], v[72:75]
	v_mfma_f32_16x16x32_bf16 v[68:71], v[168:171], v[208:211], v[68:71]
	v_mfma_f32_16x16x32_bf16 v[64:67], v[176:179], v[208:211], v[64:67]
	v_mfma_f32_16x16x32_bf16 v[116:119], v[172:175], v[188:191], v[116:119]
	v_mfma_f32_16x16x32_bf16 v[112:115], v[180:183], v[188:191], v[112:115]
	v_mfma_f32_16x16x32_bf16 v[100:103], v[172:175], v[196:199], v[100:103]
	v_mfma_f32_16x16x32_bf16 v[96:99], v[180:183], v[196:199], v[96:99]
	s_barrier
	v_mfma_f32_16x16x32_bf16 v[80:83], v[172:175], v[204:207], v[80:83]
	v_mfma_f32_16x16x32_bf16 v[72:75], v[180:183], v[204:207], v[72:75]
	v_mfma_f32_16x16x32_bf16 v[68:71], v[172:175], v[212:215], v[68:71]
	v_mfma_f32_16x16x32_bf16 v[64:67], v[180:183], v[212:215], v[64:67]
	s_setprio 0
	s_add_i32 s68, s46, s36
	v_lshl_add_u64 v[216:217], s[26:27], 0, v[132:133]
	s_mov_b32 m0, s68
	ds_read_b128 v[184:187], v157 offset:16384
	ds_read_b128 v[188:191], v157 offset:17408
	ds_read_b128 v[192:195], v157 offset:18432
	ds_read_b128 v[196:199], v157 offset:19456
	ds_read_b128 v[200:203], v157 offset:20480
	ds_read_b128 v[204:207], v157 offset:21504
	ds_read_b128 v[208:211], v157 offset:22528
	ds_read_b128 v[212:215], v157 offset:23552
	global_load_lds_dwordx4 v[216:217], off
	s_add_i32 m0, s68, 0x2000
	s_add_u32 s68, s26, 0x80000
	v_lshl_add_u64 v[218:219], s[26:27], 0, v[128:129]
	s_addc_u32 s69, s27, 0
	s_add_i32 s76, s47, s36
	global_load_lds_dwordx4 v[218:219], off
	v_lshl_add_u64 v[220:221], s[68:69], 0, v[132:133]
	s_mov_b32 m0, s76
	v_lshl_add_u64 v[222:223], s[28:29], 0, v[130:131]
	global_load_lds_dwordx4 v[220:221], off
	v_lshl_add_u64 v[220:221], s[68:69], 0, v[128:129]
	s_add_i32 m0, s76, 0x2000
	s_nop 0
	global_load_lds_dwordx4 v[220:221], off
	v_lshl_add_u64 v[220:221], s[28:29], 0, v[134:135]
	s_mov_b32 m0, s23
	s_nop 0
	global_load_lds_dwordx4 v[220:221], off
	s_mov_b32 m0, s38
	s_nop 0
	global_load_lds_dwordx4 v[222:223], off
	s_waitcnt vmcnt(8)
	s_waitcnt lgkmcnt(0)
	s_barrier
	s_setprio 1
	s_waitcnt lgkmcnt(0)
	v_mfma_f32_16x16x32_bf16 v[60:63], v[144:147], v[184:187], v[60:63]
	v_mfma_f32_16x16x32_bf16 v[56:59], v[160:163], v[184:187], v[56:59]
	v_mfma_f32_16x16x32_bf16 v[44:47], v[144:147], v[192:195], v[44:47]
	v_mfma_f32_16x16x32_bf16 v[40:43], v[160:163], v[192:195], v[40:43]
	v_mfma_f32_16x16x32_bf16 v[28:31], v[144:147], v[200:203], v[28:31]
	v_mfma_f32_16x16x32_bf16 v[24:27], v[160:163], v[200:203], v[24:27]
	v_mfma_f32_16x16x32_bf16 v[12:15], v[144:147], v[208:211], v[12:15]
	v_mfma_f32_16x16x32_bf16 v[8:11], v[160:163], v[208:211], v[8:11]
	v_mfma_f32_16x16x32_bf16 v[60:63], v[148:151], v[188:191], v[60:63]
	v_mfma_f32_16x16x32_bf16 v[56:59], v[164:167], v[188:191], v[56:59]
	v_mfma_f32_16x16x32_bf16 v[44:47], v[148:151], v[196:199], v[44:47]
	v_mfma_f32_16x16x32_bf16 v[40:43], v[164:167], v[196:199], v[40:43]
	v_mfma_f32_16x16x32_bf16 v[28:31], v[148:151], v[204:207], v[28:31]
	v_mfma_f32_16x16x32_bf16 v[24:27], v[164:167], v[204:207], v[24:27]
	v_mfma_f32_16x16x32_bf16 v[12:15], v[148:151], v[212:215], v[12:15]
	v_mfma_f32_16x16x32_bf16 v[8:11], v[164:167], v[212:215], v[8:11]
	s_setprio 0
	s_setprio 1
	v_mfma_f32_16x16x32_bf16 v[52:55], v[168:171], v[184:187], v[52:55]
	v_mfma_f32_16x16x32_bf16 v[48:51], v[176:179], v[184:187], v[48:51]
	v_mfma_f32_16x16x32_bf16 v[36:39], v[168:171], v[192:195], v[36:39]
	v_mfma_f32_16x16x32_bf16 v[32:35], v[176:179], v[192:195], v[32:35]
	v_mfma_f32_16x16x32_bf16 v[20:23], v[168:171], v[200:203], v[20:23]
	v_mfma_f32_16x16x32_bf16 v[16:19], v[176:179], v[200:203], v[16:19]
	v_mfma_f32_16x16x32_bf16 v[4:7], v[168:171], v[208:211], v[4:7]
	v_mfma_f32_16x16x32_bf16 v[0:3], v[176:179], v[208:211], v[0:3]
	v_mfma_f32_16x16x32_bf16 v[52:55], v[172:175], v[188:191], v[52:55]
	v_mfma_f32_16x16x32_bf16 v[48:51], v[180:183], v[188:191], v[48:51]
	v_mfma_f32_16x16x32_bf16 v[36:39], v[172:175], v[196:199], v[36:39]
	v_mfma_f32_16x16x32_bf16 v[32:35], v[180:183], v[196:199], v[32:35]
	s_barrier
	v_mfma_f32_16x16x32_bf16 v[20:23], v[172:175], v[204:207], v[20:23]
	v_mfma_f32_16x16x32_bf16 v[16:19], v[180:183], v[204:207], v[16:19]
	v_mfma_f32_16x16x32_bf16 v[4:7], v[172:175], v[212:215], v[4:7]
	v_mfma_f32_16x16x32_bf16 v[0:3], v[180:183], v[212:215], v[0:3]
	s_setprio 0
	s_add_i32 s68, 0, 0x18000
	s_add_i32 s69, 0, 0x1c000
	v_add_u32_e32 v164, s68, v153
	v_add_u32_e32 v180, s69, v153
	ds_read_b128 v[144:147], v164
	ds_read_b128 v[148:151], v164 offset:1024
	ds_read_b128 v[160:163], v164 offset:2048
	ds_read_b128 v[164:167], v164 offset:3072
	ds_read_b128 v[168:171], v180
	ds_read_b128 v[172:175], v180 offset:1024
	ds_read_b128 v[176:179], v180 offset:2048
	ds_read_b128 v[180:183], v180 offset:3072
	s_add_u32 s28, s28, 0x80000
	s_addc_u32 s29, s29, 0
	s_mov_b32 m0, s39
	v_lshl_add_u64 v[224:225], s[28:29], 0, v[134:135]
	ds_read_b128 v[184:187], v157 offset:32768
	ds_read_b128 v[188:191], v157 offset:33792
	ds_read_b128 v[192:195], v157 offset:34816
	ds_read_b128 v[196:199], v157 offset:35840
	ds_read_b128 v[200:203], v157 offset:36864
	ds_read_b128 v[204:207], v157 offset:37888
	ds_read_b128 v[208:211], v157 offset:38912
	ds_read_b128 v[212:215], v157 offset:39936
	global_load_lds_dwordx4 v[224:225], off
	v_lshl_add_u64 v[224:225], s[28:29], 0, v[130:131]
	s_mov_b32 m0, s40
	s_nop 0
	global_load_lds_dwordx4 v[224:225], off
	s_waitcnt vmcnt(8)
	s_waitcnt lgkmcnt(0)
	s_barrier
	s_setprio 1
	s_waitcnt lgkmcnt(0)
	v_mfma_f32_16x16x32_bf16 v[124:127], v[144:147], v[184:187], v[124:127]
	v_mfma_f32_16x16x32_bf16 v[120:123], v[160:163], v[184:187], v[120:123]
	v_mfma_f32_16x16x32_bf16 v[108:111], v[144:147], v[192:195], v[108:111]
	v_mfma_f32_16x16x32_bf16 v[104:107], v[160:163], v[192:195], v[104:107]
	v_mfma_f32_16x16x32_bf16 v[92:95], v[144:147], v[200:203], v[92:95]
	v_mfma_f32_16x16x32_bf16 v[88:91], v[160:163], v[200:203], v[88:91]
	v_mfma_f32_16x16x32_bf16 v[84:87], v[144:147], v[208:211], v[84:87]
	v_mfma_f32_16x16x32_bf16 v[76:79], v[160:163], v[208:211], v[76:79]
	v_mfma_f32_16x16x32_bf16 v[124:127], v[148:151], v[188:191], v[124:127]
	v_mfma_f32_16x16x32_bf16 v[120:123], v[164:167], v[188:191], v[120:123]
	v_mfma_f32_16x16x32_bf16 v[108:111], v[148:151], v[196:199], v[108:111]
	v_mfma_f32_16x16x32_bf16 v[104:107], v[164:167], v[196:199], v[104:107]
	v_mfma_f32_16x16x32_bf16 v[92:95], v[148:151], v[204:207], v[92:95]
	v_mfma_f32_16x16x32_bf16 v[88:91], v[164:167], v[204:207], v[88:91]
	v_mfma_f32_16x16x32_bf16 v[84:87], v[148:151], v[212:215], v[84:87]
	v_mfma_f32_16x16x32_bf16 v[76:79], v[164:167], v[212:215], v[76:79]
	s_setprio 0
	s_setprio 1
	v_mfma_f32_16x16x32_bf16 v[116:119], v[168:171], v[184:187], v[116:119]
	v_mfma_f32_16x16x32_bf16 v[112:115], v[176:179], v[184:187], v[112:115]
	v_mfma_f32_16x16x32_bf16 v[100:103], v[168:171], v[192:195], v[100:103]
	v_mfma_f32_16x16x32_bf16 v[96:99], v[176:179], v[192:195], v[96:99]
	v_mfma_f32_16x16x32_bf16 v[80:83], v[168:171], v[200:203], v[80:83]
	v_mfma_f32_16x16x32_bf16 v[72:75], v[176:179], v[200:203], v[72:75]
	v_mfma_f32_16x16x32_bf16 v[68:71], v[168:171], v[208:211], v[68:71]
	v_mfma_f32_16x16x32_bf16 v[64:67], v[176:179], v[208:211], v[64:67]
	v_mfma_f32_16x16x32_bf16 v[116:119], v[172:175], v[188:191], v[116:119]
	v_mfma_f32_16x16x32_bf16 v[112:115], v[180:183], v[188:191], v[112:115]
	v_mfma_f32_16x16x32_bf16 v[100:103], v[172:175], v[196:199], v[100:103]
	v_mfma_f32_16x16x32_bf16 v[96:99], v[180:183], v[196:199], v[96:99]
	s_barrier
	v_mfma_f32_16x16x32_bf16 v[80:83], v[172:175], v[204:207], v[80:83]
	v_mfma_f32_16x16x32_bf16 v[72:75], v[180:183], v[204:207], v[72:75]
	v_mfma_f32_16x16x32_bf16 v[68:71], v[172:175], v[212:215], v[68:71]
	v_mfma_f32_16x16x32_bf16 v[64:67], v[180:183], v[212:215], v[64:67]
	s_setprio 0
	s_add_i32 s28, s68, s36
	v_lshl_add_u64 v[216:217], v[216:217], 0, s[8:9]
	s_mov_b32 m0, s28
	ds_read_b128 v[184:187], v157 offset:49152
	ds_read_b128 v[188:191], v157 offset:50176
	ds_read_b128 v[192:195], v157 offset:51200
	ds_read_b128 v[196:199], v157 offset:52224
	ds_read_b128 v[200:203], v157 offset:53248
	ds_read_b128 v[204:207], v157 offset:54272
	ds_read_b128 v[208:211], v157 offset:55296
	ds_read_b128 v[212:215], v157 offset:56320
	global_load_lds_dwordx4 v[216:217], off
	s_add_i32 m0, s28, 0x2000
	s_add_u32 s26, s26, 0x80080
	v_lshl_add_u64 v[216:217], v[218:219], 0, s[8:9]
	s_addc_u32 s27, s27, 0
	s_add_i32 s28, s69, s36
	global_load_lds_dwordx4 v[216:217], off
	v_lshl_add_u64 v[216:217], s[26:27], 0, v[132:133]
	s_mov_b32 m0, s28
	s_nop 0
	global_load_lds_dwordx4 v[216:217], off
	v_lshl_add_u64 v[216:217], s[26:27], 0, v[128:129]
	s_add_i32 m0, s28, 0x2000
	s_nop 0
	global_load_lds_dwordx4 v[216:217], off
	v_lshl_add_u64 v[216:217], v[220:221], 0, s[8:9]
	s_mov_b32 m0, s43
	s_nop 0
	global_load_lds_dwordx4 v[216:217], off
	v_lshl_add_u64 v[216:217], v[222:223], 0, s[8:9]
	s_mov_b32 m0, s44
	s_nop 0
	global_load_lds_dwordx4 v[216:217], off
	s_waitcnt vmcnt(8)
	s_waitcnt lgkmcnt(0)
	s_barrier
	s_setprio 1
	s_waitcnt lgkmcnt(0)
	v_mfma_f32_16x16x32_bf16 v[60:63], v[144:147], v[184:187], v[60:63]
	v_mfma_f32_16x16x32_bf16 v[56:59], v[160:163], v[184:187], v[56:59]
	v_mfma_f32_16x16x32_bf16 v[44:47], v[144:147], v[192:195], v[44:47]
	v_mfma_f32_16x16x32_bf16 v[40:43], v[160:163], v[192:195], v[40:43]
	v_mfma_f32_16x16x32_bf16 v[28:31], v[144:147], v[200:203], v[28:31]
	v_mfma_f32_16x16x32_bf16 v[24:27], v[160:163], v[200:203], v[24:27]
	v_mfma_f32_16x16x32_bf16 v[12:15], v[144:147], v[208:211], v[12:15]
	v_mfma_f32_16x16x32_bf16 v[8:11], v[160:163], v[208:211], v[8:11]
	v_mfma_f32_16x16x32_bf16 v[60:63], v[148:151], v[188:191], v[60:63]
	v_mfma_f32_16x16x32_bf16 v[56:59], v[164:167], v[188:191], v[56:59]
	v_mfma_f32_16x16x32_bf16 v[44:47], v[148:151], v[196:199], v[44:47]
	v_mfma_f32_16x16x32_bf16 v[40:43], v[164:167], v[196:199], v[40:43]
	v_mfma_f32_16x16x32_bf16 v[28:31], v[148:151], v[204:207], v[28:31]
	v_mfma_f32_16x16x32_bf16 v[24:27], v[164:167], v[204:207], v[24:27]
	v_mfma_f32_16x16x32_bf16 v[12:15], v[148:151], v[212:215], v[12:15]
	v_mfma_f32_16x16x32_bf16 v[8:11], v[164:167], v[212:215], v[8:11]
	s_setprio 0
	s_setprio 1
	v_mfma_f32_16x16x32_bf16 v[52:55], v[168:171], v[184:187], v[52:55]
	v_mfma_f32_16x16x32_bf16 v[48:51], v[176:179], v[184:187], v[48:51]
	v_mfma_f32_16x16x32_bf16 v[36:39], v[168:171], v[192:195], v[36:39]
	v_mfma_f32_16x16x32_bf16 v[32:35], v[176:179], v[192:195], v[32:35]
	v_mfma_f32_16x16x32_bf16 v[20:23], v[168:171], v[200:203], v[20:23]
	v_mfma_f32_16x16x32_bf16 v[16:19], v[176:179], v[200:203], v[16:19]
	v_mfma_f32_16x16x32_bf16 v[4:7], v[168:171], v[208:211], v[4:7]
	v_mfma_f32_16x16x32_bf16 v[0:3], v[176:179], v[208:211], v[0:3]
	v_mfma_f32_16x16x32_bf16 v[52:55], v[172:175], v[188:191], v[52:55]
	v_mfma_f32_16x16x32_bf16 v[48:51], v[180:183], v[188:191], v[48:51]
	v_mfma_f32_16x16x32_bf16 v[36:39], v[172:175], v[196:199], v[36:39]
	v_mfma_f32_16x16x32_bf16 v[32:35], v[180:183], v[196:199], v[32:35]
	s_barrier
	v_mfma_f32_16x16x32_bf16 v[20:23], v[172:175], v[204:207], v[20:23]
	v_mfma_f32_16x16x32_bf16 v[16:19], v[180:183], v[204:207], v[16:19]
	v_mfma_f32_16x16x32_bf16 v[4:7], v[172:175], v[212:215], v[4:7]
	v_mfma_f32_16x16x32_bf16 v[0:3], v[180:183], v[212:215], v[0:3]
	s_setprio 0
	s_add_i32 s57, s57, 2
	s_add_u32 s24, s24, 0x100
	s_addc_u32 s25, s25, 0
	s_add_u32 s55, s55, 0x100
	s_addc_u32 s56, s56, 0
	s_cmp_gt_u32 s57, 29
	s_cbranch_scc0 .LBB0_274
	s_and_b64 vcc, exec, s[10:11]
	s_cbranch_vccz .LBB0_277
	s_barrier

.LBB0_533:
	ds_read_b128 v[146:149], v140
	ds_read_b128 v[150:153], v140 offset:1024
	ds_read_b128 v[154:157], v140 offset:2048
	ds_read_b128 v[160:163], v140 offset:3072
	ds_read_b128 v[164:167], v141
	ds_read_b128 v[168:171], v141 offset:1024
	ds_read_b128 v[172:175], v141 offset:2048
	ds_read_b128 v[176:179], v141 offset:3072
	s_add_u32 s34, s30, 0xfff80080
	s_addc_u32 s35, s31, -1
	s_cmp_eq_u32 s69, 12
	s_cselect_b32 s37, s19, s35
	s_cselect_b32 s36, s23, s34
	s_cselect_b32 s35, s25, s68
	s_cselect_b32 s34, s60, s61
	v_lshl_add_u64 v[212:213], s[30:31], 0, v[132:133]
	s_add_i32 m0, s9, 0xc000
	ds_read_b128 v[180:183], v142
	ds_read_b128 v[184:187], v142 offset:1024
	ds_read_b128 v[188:191], v142 offset:2048
	ds_read_b128 v[192:195], v142 offset:3072
	ds_read_b128 v[196:199], v142 offset:4096
	ds_read_b128 v[200:203], v142 offset:5120
	ds_read_b128 v[204:207], v142 offset:6144
	ds_read_b128 v[208:211], v142 offset:7168
	global_load_lds_dwordx4 v[212:213], off
	v_lshl_add_u64 v[212:213], s[30:31], 0, v[134:135]
	s_add_i32 m0, s9, 0xe000
	s_nop 0
	global_load_lds_dwordx4 v[212:213], off
	s_waitcnt vmcnt(8)
	s_waitcnt lgkmcnt(0)
	s_barrier
	s_setprio 1
	s_waitcnt lgkmcnt(0)
	v_mfma_f32_16x16x32_bf16 v[124:127], v[146:149], v[180:183], v[124:127]
	v_mfma_f32_16x16x32_bf16 v[120:123], v[154:157], v[180:183], v[120:123]
	v_mfma_f32_16x16x32_bf16 v[116:119], v[146:149], v[188:191], v[116:119]
	v_mfma_f32_16x16x32_bf16 v[112:115], v[154:157], v[188:191], v[112:115]
	v_mfma_f32_16x16x32_bf16 v[104:107], v[146:149], v[196:199], v[104:107]
	v_mfma_f32_16x16x32_bf16 v[96:99], v[154:157], v[196:199], v[96:99]
	v_mfma_f32_16x16x32_bf16 v[88:91], v[146:149], v[204:207], v[88:91]
	v_mfma_f32_16x16x32_bf16 v[80:83], v[154:157], v[204:207], v[80:83]
	v_mfma_f32_16x16x32_bf16 v[124:127], v[150:153], v[184:187], v[124:127]
	v_mfma_f32_16x16x32_bf16 v[120:123], v[160:163], v[184:187], v[120:123]
	v_mfma_f32_16x16x32_bf16 v[116:119], v[150:153], v[192:195], v[116:119]
	v_mfma_f32_16x16x32_bf16 v[112:115], v[160:163], v[192:195], v[112:115]
	v_mfma_f32_16x16x32_bf16 v[104:107], v[150:153], v[200:203], v[104:107]
	v_mfma_f32_16x16x32_bf16 v[96:99], v[160:163], v[200:203], v[96:99]
	v_mfma_f32_16x16x32_bf16 v[88:91], v[150:153], v[208:211], v[88:91]
	v_mfma_f32_16x16x32_bf16 v[80:83], v[160:163], v[208:211], v[80:83]
	s_setprio 0
	s_setprio 1
	v_mfma_f32_16x16x32_bf16 v[108:111], v[164:167], v[180:183], v[108:111]
	v_mfma_f32_16x16x32_bf16 v[100:103], v[172:175], v[180:183], v[100:103]
	v_mfma_f32_16x16x32_bf16 v[92:95], v[164:167], v[188:191], v[92:95]
	v_mfma_f32_16x16x32_bf16 v[84:87], v[172:175], v[188:191], v[84:87]
	v_mfma_f32_16x16x32_bf16 v[76:79], v[164:167], v[196:199], v[76:79]
	v_mfma_f32_16x16x32_bf16 v[72:75], v[172:175], v[196:199], v[72:75]
	v_mfma_f32_16x16x32_bf16 v[68:71], v[164:167], v[204:207], v[68:71]
	v_mfma_f32_16x16x32_bf16 v[64:67], v[172:175], v[204:207], v[64:67]
	v_mfma_f32_16x16x32_bf16 v[108:111], v[168:171], v[184:187], v[108:111]
	v_mfma_f32_16x16x32_bf16 v[100:103], v[176:179], v[184:187], v[100:103]
	v_mfma_f32_16x16x32_bf16 v[92:95], v[168:171], v[192:195], v[92:95]
	v_mfma_f32_16x16x32_bf16 v[84:87], v[176:179], v[192:195], v[84:87]
	s_barrier
	v_mfma_f32_16x16x32_bf16 v[76:79], v[168:171], v[200:203], v[76:79]
	v_mfma_f32_16x16x32_bf16 v[72:75], v[176:179], v[200:203], v[72:75]
	v_mfma_f32_16x16x32_bf16 v[68:71], v[168:171], v[208:211], v[68:71]
	v_mfma_f32_16x16x32_bf16 v[64:67], v[176:179], v[208:211], v[64:67]
	s_setprio 0
	s_add_i32 s76, s55, s43
	v_lshl_add_u64 v[212:213], s[34:35], 0, v[128:129]
	s_mov_b32 m0, s76
	ds_read_b128 v[180:183], v142 offset:16384
	ds_read_b128 v[184:187], v142 offset:17408
	ds_read_b128 v[188:191], v142 offset:18432
	ds_read_b128 v[192:195], v142 offset:19456
	ds_read_b128 v[196:199], v142 offset:20480
	ds_read_b128 v[200:203], v142 offset:21504
	ds_read_b128 v[204:207], v142 offset:22528
	ds_read_b128 v[208:211], v142 offset:23552
	global_load_lds_dwordx4 v[212:213], off
	s_add_i32 m0, s76, 0x2000
	s_add_u32 s76, s34, 0x80000
	v_lshl_add_u64 v[214:215], s[34:35], 0, v[130:131]
	s_addc_u32 s77, s35, 0
	s_add_i32 s78, s56, s43
	global_load_lds_dwordx4 v[214:215], off
	v_lshl_add_u64 v[216:217], s[76:77], 0, v[128:129]
	s_mov_b32 m0, s78
	v_lshl_add_u64 v[218:219], s[36:37], 0, v[130:131]
	global_load_lds_dwordx4 v[216:217], off
	v_lshl_add_u64 v[216:217], s[76:77], 0, v[130:131]
	s_add_i32 m0, s78, 0x2000
	s_nop 0
	global_load_lds_dwordx4 v[216:217], off
	v_lshl_add_u64 v[216:217], s[36:37], 0, v[128:129]
	s_mov_b32 m0, s9
	s_nop 0
	global_load_lds_dwordx4 v[216:217], off
	s_mov_b32 m0, s44
	s_nop 0
	global_load_lds_dwordx4 v[218:219], off
	s_waitcnt vmcnt(8)
	s_waitcnt lgkmcnt(0)
	s_barrier
	s_setprio 1
	s_waitcnt lgkmcnt(0)
	v_mfma_f32_16x16x32_bf16 v[60:63], v[146:149], v[180:183], v[60:63]
	v_mfma_f32_16x16x32_bf16 v[56:59], v[154:157], v[180:183], v[56:59]
	v_mfma_f32_16x16x32_bf16 v[52:55], v[146:149], v[188:191], v[52:55]
	v_mfma_f32_16x16x32_bf16 v[48:51], v[154:157], v[188:191], v[48:51]
	v_mfma_f32_16x16x32_bf16 v[40:43], v[146:149], v[196:199], v[40:43]
	v_mfma_f32_16x16x32_bf16 v[32:35], v[154:157], v[196:199], v[32:35]
	v_mfma_f32_16x16x32_bf16 v[24:27], v[146:149], v[204:207], v[24:27]
	v_mfma_f32_16x16x32_bf16 v[16:19], v[154:157], v[204:207], v[16:19]
	v_mfma_f32_16x16x32_bf16 v[60:63], v[150:153], v[184:187], v[60:63]
	v_mfma_f32_16x16x32_bf16 v[56:59], v[160:163], v[184:187], v[56:59]
	v_mfma_f32_16x16x32_bf16 v[52:55], v[150:153], v[192:195], v[52:55]
	v_mfma_f32_16x16x32_bf16 v[48:51], v[160:163], v[192:195], v[48:51]
	v_mfma_f32_16x16x32_bf16 v[40:43], v[150:153], v[200:203], v[40:43]
	v_mfma_f32_16x16x32_bf16 v[32:35], v[160:163], v[200:203], v[32:35]
	v_mfma_f32_16x16x32_bf16 v[24:27], v[150:153], v[208:211], v[24:27]
	v_mfma_f32_16x16x32_bf16 v[16:19], v[160:163], v[208:211], v[16:19]
	s_setprio 0
	s_setprio 1
	v_mfma_f32_16x16x32_bf16 v[44:47], v[164:167], v[180:183], v[44:47]
	v_mfma_f32_16x16x32_bf16 v[36:39], v[172:175], v[180:183], v[36:39]
	v_mfma_f32_16x16x32_bf16 v[28:31], v[164:167], v[188:191], v[28:31]
	v_mfma_f32_16x16x32_bf16 v[20:23], v[172:175], v[188:191], v[20:23]
	v_mfma_f32_16x16x32_bf16 v[12:15], v[164:167], v[196:199], v[12:15]
	v_mfma_f32_16x16x32_bf16 v[8:11], v[172:175], v[196:199], v[8:11]
	v_mfma_f32_16x16x32_bf16 v[4:7], v[164:167], v[204:207], v[4:7]
	v_mfma_f32_16x16x32_bf16 v[0:3], v[172:175], v[204:207], v[0:3]
	v_mfma_f32_16x16x32_bf16 v[44:47], v[168:171], v[184:187], v[44:47]
	v_mfma_f32_16x16x32_bf16 v[36:39], v[176:179], v[184:187], v[36:39]
	v_mfma_f32_16x16x32_bf16 v[28:31], v[168:171], v[192:195], v[28:31]
	v_mfma_f32_16x16x32_bf16 v[20:23], v[176:179], v[192:195], v[20:23]
	s_barrier
	v_mfma_f32_16x16x32_bf16 v[12:15], v[168:171], v[200:203], v[12:15]
	v_mfma_f32_16x16x32_bf16 v[8:11], v[176:179], v[200:203], v[8:11]
	v_mfma_f32_16x16x32_bf16 v[4:7], v[168:171], v[208:211], v[4:7]
	v_mfma_f32_16x16x32_bf16 v[0:3], v[176:179], v[208:211], v[0:3]
	s_setprio 0
	s_add_i32 s76, 0, 0x18000
	v_add_u32_e32 v143, s76, v138
	s_add_i32 s77, 0, 0x1c000
	ds_read_b128 v[146:149], v143
	ds_read_b128 v[150:153], v143 offset:1024
	ds_read_b128 v[154:157], v143 offset:2048
	ds_read_b128 v[160:163], v143 offset:3072
	v_add_u32_e32 v143, s77, v138
	ds_read_b128 v[164:167], v143
	ds_read_b128 v[168:171], v143 offset:1024
	ds_read_b128 v[172:175], v143 offset:2048
	ds_read_b128 v[176:179], v143 offset:3072
	s_add_u32 s36, s36, 0x80000
	s_addc_u32 s37, s37, 0
	s_mov_b32 m0, s45
	v_lshl_add_u64 v[220:221], s[36:37], 0, v[128:129]
	ds_read_b128 v[180:183], v142 offset:32768
	ds_read_b128 v[184:187], v142 offset:33792
	ds_read_b128 v[188:191], v142 offset:34816
	ds_read_b128 v[192:195], v142 offset:35840
	ds_read_b128 v[196:199], v142 offset:36864
	ds_read_b128 v[200:203], v142 offset:37888
	ds_read_b128 v[204:207], v142 offset:38912
	ds_read_b128 v[208:211], v142 offset:39936
	global_load_lds_dwordx4 v[220:221], off
	v_lshl_add_u64 v[220:221], s[36:37], 0, v[130:131]
	s_mov_b32 m0, s46
	s_nop 0
	global_load_lds_dwordx4 v[220:221], off
	s_waitcnt vmcnt(8)
	s_waitcnt lgkmcnt(0)
	s_barrier
	s_setprio 1
	s_waitcnt lgkmcnt(0)
	v_mfma_f32_16x16x32_bf16 v[124:127], v[146:149], v[180:183], v[124:127]
	v_mfma_f32_16x16x32_bf16 v[120:123], v[154:157], v[180:183], v[120:123]
	v_mfma_f32_16x16x32_bf16 v[116:119], v[146:149], v[188:191], v[116:119]
	v_mfma_f32_16x16x32_bf16 v[112:115], v[154:157], v[188:191], v[112:115]
	v_mfma_f32_16x16x32_bf16 v[104:107], v[146:149], v[196:199], v[104:107]
	v_mfma_f32_16x16x32_bf16 v[96:99], v[154:157], v[196:199], v[96:99]
	v_mfma_f32_16x16x32_bf16 v[88:91], v[146:149], v[204:207], v[88:91]
	v_mfma_f32_16x16x32_bf16 v[80:83], v[154:157], v[204:207], v[80:83]
	v_mfma_f32_16x16x32_bf16 v[124:127], v[150:153], v[184:187], v[124:127]
	v_mfma_f32_16x16x32_bf16 v[120:123], v[160:163], v[184:187], v[120:123]
	v_mfma_f32_16x16x32_bf16 v[116:119], v[150:153], v[192:195], v[116:119]
	v_mfma_f32_16x16x32_bf16 v[112:115], v[160:163], v[192:195], v[112:115]
	v_mfma_f32_16x16x32_bf16 v[104:107], v[150:153], v[200:203], v[104:107]
	v_mfma_f32_16x16x32_bf16 v[96:99], v[160:163], v[200:203], v[96:99]
	v_mfma_f32_16x16x32_bf16 v[88:91], v[150:153], v[208:211], v[88:91]
	v_mfma_f32_16x16x32_bf16 v[80:83], v[160:163], v[208:211], v[80:83]
	s_setprio 0
	s_setprio 1
	v_mfma_f32_16x16x32_bf16 v[108:111], v[164:167], v[180:183], v[108:111]
	v_mfma_f32_16x16x32_bf16 v[100:103], v[172:175], v[180:183], v[100:103]
	v_mfma_f32_16x16x32_bf16 v[92:95], v[164:167], v[188:191], v[92:95]
	v_mfma_f32_16x16x32_bf16 v[84:87], v[172:175], v[188:191], v[84:87]
	v_mfma_f32_16x16x32_bf16 v[76:79], v[164:167], v[196:199], v[76:79]
	v_mfma_f32_16x16x32_bf16 v[72:75], v[172:175], v[196:199], v[72:75]
	v_mfma_f32_16x16x32_bf16 v[68:71], v[164:167], v[204:207], v[68:71]
	v_mfma_f32_16x16x32_bf16 v[64:67], v[172:175], v[204:207], v[64:67]
	v_mfma_f32_16x16x32_bf16 v[108:111], v[168:171], v[184:187], v[108:111]
	v_mfma_f32_16x16x32_bf16 v[100:103], v[176:179], v[184:187], v[100:103]
	v_mfma_f32_16x16x32_bf16 v[92:95], v[168:171], v[192:195], v[92:95]
	v_mfma_f32_16x16x32_bf16 v[84:87], v[176:179], v[192:195], v[84:87]
	s_barrier
	v_mfma_f32_16x16x32_bf16 v[76:79], v[168:171], v[200:203], v[76:79]
	v_mfma_f32_16x16x32_bf16 v[72:75], v[176:179], v[200:203], v[72:75]
	v_mfma_f32_16x16x32_bf16 v[68:71], v[168:171], v[208:211], v[68:71]
	v_mfma_f32_16x16x32_bf16 v[64:67], v[176:179], v[208:211], v[64:67]
	s_setprio 0
	s_add_i32 s36, s76, s43
	v_lshl_add_u64 v[212:213], v[212:213], 0, s[6:7]
	s_mov_b32 m0, s36
	ds_read_b128 v[180:183], v142 offset:49152
	ds_read_b128 v[184:187], v142 offset:50176
	ds_read_b128 v[188:191], v142 offset:51200
	ds_read_b128 v[192:195], v142 offset:52224
	ds_read_b128 v[196:199], v142 offset:53248
	ds_read_b128 v[200:203], v142 offset:54272
	ds_read_b128 v[204:207], v142 offset:55296
	ds_read_b128 v[208:211], v142 offset:56320
	global_load_lds_dwordx4 v[212:213], off
	s_add_i32 m0, s36, 0x2000
	s_add_u32 s34, s34, 0x80080
	v_lshl_add_u64 v[212:213], v[214:215], 0, s[6:7]
	s_addc_u32 s35, s35, 0
	s_add_i32 s36, s77, s43
	global_load_lds_dwordx4 v[212:213], off
	v_lshl_add_u64 v[212:213], s[34:35], 0, v[128:129]
	s_mov_b32 m0, s36
	s_nop 0
	global_load_lds_dwordx4 v[212:213], off
	v_lshl_add_u64 v[212:213], s[34:35], 0, v[130:131]
	s_add_i32 m0, s36, 0x2000
	s_nop 0
	global_load_lds_dwordx4 v[212:213], off
	v_lshl_add_u64 v[212:213], v[216:217], 0, s[6:7]
	s_mov_b32 m0, s52
	s_nop 0
	global_load_lds_dwordx4 v[212:213], off
	v_lshl_add_u64 v[212:213], v[218:219], 0, s[6:7]
	s_mov_b32 m0, s53
	s_nop 0
	global_load_lds_dwordx4 v[212:213], off
	s_waitcnt vmcnt(8)
	s_waitcnt lgkmcnt(0)
	s_barrier
	s_setprio 1
	s_waitcnt lgkmcnt(0)
	v_mfma_f32_16x16x32_bf16 v[60:63], v[146:149], v[180:183], v[60:63]
	v_mfma_f32_16x16x32_bf16 v[56:59], v[154:157], v[180:183], v[56:59]
	v_mfma_f32_16x16x32_bf16 v[52:55], v[146:149], v[188:191], v[52:55]
	v_mfma_f32_16x16x32_bf16 v[48:51], v[154:157], v[188:191], v[48:51]
	v_mfma_f32_16x16x32_bf16 v[40:43], v[146:149], v[196:199], v[40:43]
	v_mfma_f32_16x16x32_bf16 v[32:35], v[154:157], v[196:199], v[32:35]
	v_mfma_f32_16x16x32_bf16 v[24:27], v[146:149], v[204:207], v[24:27]
	v_mfma_f32_16x16x32_bf16 v[16:19], v[154:157], v[204:207], v[16:19]
	v_mfma_f32_16x16x32_bf16 v[60:63], v[150:153], v[184:187], v[60:63]
	v_mfma_f32_16x16x32_bf16 v[56:59], v[160:163], v[184:187], v[56:59]
	v_mfma_f32_16x16x32_bf16 v[52:55], v[150:153], v[192:195], v[52:55]
	v_mfma_f32_16x16x32_bf16 v[48:51], v[160:163], v[192:195], v[48:51]
	v_mfma_f32_16x16x32_bf16 v[40:43], v[150:153], v[200:203], v[40:43]
	v_mfma_f32_16x16x32_bf16 v[32:35], v[160:163], v[200:203], v[32:35]
	v_mfma_f32_16x16x32_bf16 v[24:27], v[150:153], v[208:211], v[24:27]
	v_mfma_f32_16x16x32_bf16 v[16:19], v[160:163], v[208:211], v[16:19]
	s_setprio 0
	s_setprio 1
	v_mfma_f32_16x16x32_bf16 v[44:47], v[164:167], v[180:183], v[44:47]
	v_mfma_f32_16x16x32_bf16 v[36:39], v[172:175], v[180:183], v[36:39]
	v_mfma_f32_16x16x32_bf16 v[28:31], v[164:167], v[188:191], v[28:31]
	v_mfma_f32_16x16x32_bf16 v[20:23], v[172:175], v[188:191], v[20:23]
	v_mfma_f32_16x16x32_bf16 v[12:15], v[164:167], v[196:199], v[12:15]
	v_mfma_f32_16x16x32_bf16 v[8:11], v[172:175], v[196:199], v[8:11]
	v_mfma_f32_16x16x32_bf16 v[4:7], v[164:167], v[204:207], v[4:7]
	v_mfma_f32_16x16x32_bf16 v[0:3], v[172:175], v[204:207], v[0:3]
	v_mfma_f32_16x16x32_bf16 v[44:47], v[168:171], v[184:187], v[44:47]
	v_mfma_f32_16x16x32_bf16 v[36:39], v[176:179], v[184:187], v[36:39]
	v_mfma_f32_16x16x32_bf16 v[28:31], v[168:171], v[192:195], v[28:31]
	v_mfma_f32_16x16x32_bf16 v[20:23], v[176:179], v[192:195], v[20:23]
	s_barrier
	v_mfma_f32_16x16x32_bf16 v[12:15], v[168:171], v[200:203], v[12:15]
	v_mfma_f32_16x16x32_bf16 v[8:11], v[176:179], v[200:203], v[8:11]
	v_mfma_f32_16x16x32_bf16 v[4:7], v[168:171], v[208:211], v[4:7]
	v_mfma_f32_16x16x32_bf16 v[0:3], v[176:179], v[208:211], v[0:3]
	s_setprio 0
	s_add_i32 s69, s69, 2
	s_add_u32 s30, s30, 0x100
	s_addc_u32 s31, s31, 0
	s_add_u32 s61, s61, 0x100
	s_addc_u32 s68, s68, 0
	s_cmp_gt_u32 s69, 13
	s_cbranch_scc0 .LBB0_533
	s_and_b64 vcc, exec, s[10:11]
	s_cbranch_vccz .LBB0_536
	s_barrier

.LBB0_1079:
	ds_read_b128 v[144:147], v151
	ds_read_b128 v[160:163], v151 offset:1024
	ds_read_b128 v[164:167], v151 offset:2048
	ds_read_b128 v[168:171], v151 offset:3072
	ds_read_b128 v[172:175], v152
	ds_read_b128 v[176:179], v152 offset:1024
	ds_read_b128 v[180:183], v152 offset:2048
	ds_read_b128 v[184:187], v152 offset:3072
	s_add_u32 s26, s24, 0xffe80080
	s_addc_u32 s27, s25, -1
	s_cmp_eq_u32 s51, 28
	s_cselect_b32 s29, s5, s27
	s_cselect_b32 s28, s4, s26
	s_cselect_b32 s27, s17, s50
	s_cselect_b32 s26, s19, s23
	v_lshl_add_u64 v[156:157], s[24:25], 0, v[136:137]
	s_add_i32 m0, s35, 0xc000
	ds_read_b128 v[188:191], v153
	ds_read_b128 v[192:195], v153 offset:1024
	ds_read_b128 v[196:199], v153 offset:2048
	ds_read_b128 v[200:203], v153 offset:3072
	ds_read_b128 v[204:207], v153 offset:4096
	ds_read_b128 v[208:211], v153 offset:5120
	ds_read_b128 v[212:215], v153 offset:6144
	ds_read_b128 v[216:219], v153 offset:7168
	global_load_lds_dwordx4 v[156:157], off
	v_lshl_add_u64 v[156:157], s[24:25], 0, v[138:139]
	s_add_i32 m0, s35, 0xe000
	s_nop 0
	global_load_lds_dwordx4 v[156:157], off
	s_waitcnt vmcnt(8)
	s_waitcnt lgkmcnt(0)
	s_barrier
	s_setprio 1
	s_waitcnt lgkmcnt(0)
	v_mfma_f32_16x16x32_bf16 v[124:127], v[144:147], v[188:191], v[124:127]
	v_mfma_f32_16x16x32_bf16 v[120:123], v[164:167], v[188:191], v[120:123]
	v_mfma_f32_16x16x32_bf16 v[108:111], v[144:147], v[196:199], v[108:111]
	v_mfma_f32_16x16x32_bf16 v[104:107], v[164:167], v[196:199], v[104:107]
	v_mfma_f32_16x16x32_bf16 v[92:95], v[144:147], v[204:207], v[92:95]
	v_mfma_f32_16x16x32_bf16 v[88:91], v[164:167], v[204:207], v[88:91]
	v_mfma_f32_16x16x32_bf16 v[76:79], v[144:147], v[212:215], v[76:79]
	v_mfma_f32_16x16x32_bf16 v[72:75], v[164:167], v[212:215], v[72:75]
	v_mfma_f32_16x16x32_bf16 v[124:127], v[160:163], v[192:195], v[124:127]
	v_mfma_f32_16x16x32_bf16 v[120:123], v[168:171], v[192:195], v[120:123]
	v_mfma_f32_16x16x32_bf16 v[108:111], v[160:163], v[200:203], v[108:111]
	v_mfma_f32_16x16x32_bf16 v[104:107], v[168:171], v[200:203], v[104:107]
	v_mfma_f32_16x16x32_bf16 v[92:95], v[160:163], v[208:211], v[92:95]
	v_mfma_f32_16x16x32_bf16 v[88:91], v[168:171], v[208:211], v[88:91]
	v_mfma_f32_16x16x32_bf16 v[76:79], v[160:163], v[216:219], v[76:79]
	v_mfma_f32_16x16x32_bf16 v[72:75], v[168:171], v[216:219], v[72:75]
	s_setprio 0
	s_setprio 1
	v_mfma_f32_16x16x32_bf16 v[116:119], v[172:175], v[188:191], v[116:119]
	v_mfma_f32_16x16x32_bf16 v[112:115], v[180:183], v[188:191], v[112:115]
	v_mfma_f32_16x16x32_bf16 v[100:103], v[172:175], v[196:199], v[100:103]
	v_mfma_f32_16x16x32_bf16 v[96:99], v[180:183], v[196:199], v[96:99]
	v_mfma_f32_16x16x32_bf16 v[84:87], v[172:175], v[204:207], v[84:87]
	v_mfma_f32_16x16x32_bf16 v[80:83], v[180:183], v[204:207], v[80:83]
	v_mfma_f32_16x16x32_bf16 v[68:71], v[172:175], v[212:215], v[68:71]
	v_mfma_f32_16x16x32_bf16 v[64:67], v[180:183], v[212:215], v[64:67]
	v_mfma_f32_16x16x32_bf16 v[116:119], v[176:179], v[192:195], v[116:119]
	v_mfma_f32_16x16x32_bf16 v[112:115], v[184:187], v[192:195], v[112:115]
	v_mfma_f32_16x16x32_bf16 v[100:103], v[176:179], v[200:203], v[100:103]
	v_mfma_f32_16x16x32_bf16 v[96:99], v[184:187], v[200:203], v[96:99]
	s_barrier
	v_mfma_f32_16x16x32_bf16 v[84:87], v[176:179], v[208:211], v[84:87]
	v_mfma_f32_16x16x32_bf16 v[80:83], v[184:187], v[208:211], v[80:83]
	v_mfma_f32_16x16x32_bf16 v[68:71], v[176:179], v[216:219], v[68:71]
	v_mfma_f32_16x16x32_bf16 v[64:67], v[184:187], v[216:219], v[64:67]
	s_setprio 0
	s_add_i32 s52, s44, s34
	v_lshl_add_u64 v[156:157], s[26:27], 0, v[130:131]
	s_mov_b32 m0, s52
	ds_read_b128 v[188:191], v153 offset:16384
	ds_read_b128 v[192:195], v153 offset:17408
	ds_read_b128 v[196:199], v153 offset:18432
	ds_read_b128 v[200:203], v153 offset:19456
	ds_read_b128 v[204:207], v153 offset:20480
	ds_read_b128 v[208:211], v153 offset:21504
	ds_read_b128 v[212:215], v153 offset:22528
	ds_read_b128 v[216:219], v153 offset:23552
	global_load_lds_dwordx4 v[156:157], off
	s_add_i32 m0, s52, 0x2000
	s_add_u32 s52, s26, 0x80000
	v_lshl_add_u64 v[220:221], s[26:27], 0, v[134:135]
	s_addc_u32 s53, s27, 0
	s_add_i32 s54, s45, s34
	global_load_lds_dwordx4 v[220:221], off
	v_lshl_add_u64 v[222:223], s[52:53], 0, v[130:131]
	s_mov_b32 m0, s54
	v_lshl_add_u64 v[224:225], s[28:29], 0, v[132:133]
	global_load_lds_dwordx4 v[222:223], off
	v_lshl_add_u64 v[222:223], s[52:53], 0, v[134:135]
	s_add_i32 m0, s54, 0x2000
	s_nop 0
	global_load_lds_dwordx4 v[222:223], off
	v_lshl_add_u64 v[222:223], s[28:29], 0, v[128:129]
	s_mov_b32 m0, s35
	s_nop 0
	global_load_lds_dwordx4 v[222:223], off
	s_mov_b32 m0, s36
	s_nop 0
	global_load_lds_dwordx4 v[224:225], off
	s_waitcnt vmcnt(8)
	s_waitcnt lgkmcnt(0)
	s_barrier
	s_setprio 1
	s_waitcnt lgkmcnt(0)
	v_mfma_f32_16x16x32_bf16 v[60:63], v[144:147], v[188:191], v[60:63]
	v_mfma_f32_16x16x32_bf16 v[56:59], v[164:167], v[188:191], v[56:59]
	v_mfma_f32_16x16x32_bf16 v[44:47], v[144:147], v[196:199], v[44:47]
	v_mfma_f32_16x16x32_bf16 v[40:43], v[164:167], v[196:199], v[40:43]
	v_mfma_f32_16x16x32_bf16 v[28:31], v[144:147], v[204:207], v[28:31]
	v_mfma_f32_16x16x32_bf16 v[24:27], v[164:167], v[204:207], v[24:27]
	v_mfma_f32_16x16x32_bf16 v[12:15], v[144:147], v[212:215], v[12:15]
	v_mfma_f32_16x16x32_bf16 v[8:11], v[164:167], v[212:215], v[8:11]
	v_mfma_f32_16x16x32_bf16 v[60:63], v[160:163], v[192:195], v[60:63]
	v_mfma_f32_16x16x32_bf16 v[56:59], v[168:171], v[192:195], v[56:59]
	v_mfma_f32_16x16x32_bf16 v[44:47], v[160:163], v[200:203], v[44:47]
	v_mfma_f32_16x16x32_bf16 v[40:43], v[168:171], v[200:203], v[40:43]
	v_mfma_f32_16x16x32_bf16 v[28:31], v[160:163], v[208:211], v[28:31]
	v_mfma_f32_16x16x32_bf16 v[24:27], v[168:171], v[208:211], v[24:27]
	v_mfma_f32_16x16x32_bf16 v[12:15], v[160:163], v[216:219], v[12:15]
	v_mfma_f32_16x16x32_bf16 v[8:11], v[168:171], v[216:219], v[8:11]
	s_setprio 0
	s_setprio 1
	v_mfma_f32_16x16x32_bf16 v[52:55], v[172:175], v[188:191], v[52:55]
	v_mfma_f32_16x16x32_bf16 v[48:51], v[180:183], v[188:191], v[48:51]
	v_mfma_f32_16x16x32_bf16 v[36:39], v[172:175], v[196:199], v[36:39]
	v_mfma_f32_16x16x32_bf16 v[32:35], v[180:183], v[196:199], v[32:35]
	v_mfma_f32_16x16x32_bf16 v[20:23], v[172:175], v[204:207], v[20:23]
	v_mfma_f32_16x16x32_bf16 v[16:19], v[180:183], v[204:207], v[16:19]
	v_mfma_f32_16x16x32_bf16 v[4:7], v[172:175], v[212:215], v[4:7]
	v_mfma_f32_16x16x32_bf16 v[0:3], v[180:183], v[212:215], v[0:3]
	v_mfma_f32_16x16x32_bf16 v[52:55], v[176:179], v[192:195], v[52:55]
	v_mfma_f32_16x16x32_bf16 v[48:51], v[184:187], v[192:195], v[48:51]
	v_mfma_f32_16x16x32_bf16 v[36:39], v[176:179], v[200:203], v[36:39]
	v_mfma_f32_16x16x32_bf16 v[32:35], v[184:187], v[200:203], v[32:35]
	s_barrier
	v_mfma_f32_16x16x32_bf16 v[20:23], v[176:179], v[208:211], v[20:23]
	v_mfma_f32_16x16x32_bf16 v[16:19], v[184:187], v[208:211], v[16:19]
	v_mfma_f32_16x16x32_bf16 v[4:7], v[176:179], v[216:219], v[4:7]
	v_mfma_f32_16x16x32_bf16 v[0:3], v[184:187], v[216:219], v[0:3]
	s_setprio 0
	s_add_i32 s52, 0, 0x18000
	v_add_u32_e32 v155, s52, v149
	s_add_i32 s53, 0, 0x1c000
	ds_read_b128 v[144:147], v155
	ds_read_b128 v[160:163], v155 offset:1024
	ds_read_b128 v[164:167], v155 offset:2048
	ds_read_b128 v[168:171], v155 offset:3072
	v_add_u32_e32 v155, s53, v149
	ds_read_b128 v[172:175], v155
	ds_read_b128 v[176:179], v155 offset:1024
	ds_read_b128 v[180:183], v155 offset:2048
	ds_read_b128 v[184:187], v155 offset:3072
	s_add_u32 s28, s28, 0x180000
	s_addc_u32 s29, s29, 0
	s_mov_b32 m0, s37
	v_lshl_add_u64 v[226:227], s[28:29], 0, v[128:129]
	ds_read_b128 v[188:191], v153 offset:32768
	ds_read_b128 v[192:195], v153 offset:33792
	ds_read_b128 v[196:199], v153 offset:34816
	ds_read_b128 v[200:203], v153 offset:35840
	ds_read_b128 v[204:207], v153 offset:36864
	ds_read_b128 v[208:211], v153 offset:37888
	ds_read_b128 v[212:215], v153 offset:38912
	ds_read_b128 v[216:219], v153 offset:39936
	global_load_lds_dwordx4 v[226:227], off
	v_lshl_add_u64 v[226:227], s[28:29], 0, v[132:133]
	s_mov_b32 m0, s38
	s_nop 0
	global_load_lds_dwordx4 v[226:227], off
	s_waitcnt vmcnt(8)
	s_waitcnt lgkmcnt(0)
	s_barrier
	s_setprio 1
	s_waitcnt lgkmcnt(0)
	v_mfma_f32_16x16x32_bf16 v[124:127], v[144:147], v[188:191], v[124:127]
	v_mfma_f32_16x16x32_bf16 v[120:123], v[164:167], v[188:191], v[120:123]
	v_mfma_f32_16x16x32_bf16 v[108:111], v[144:147], v[196:199], v[108:111]
	v_mfma_f32_16x16x32_bf16 v[104:107], v[164:167], v[196:199], v[104:107]
	v_mfma_f32_16x16x32_bf16 v[92:95], v[144:147], v[204:207], v[92:95]
	v_mfma_f32_16x16x32_bf16 v[88:91], v[164:167], v[204:207], v[88:91]
	v_mfma_f32_16x16x32_bf16 v[76:79], v[144:147], v[212:215], v[76:79]
	v_mfma_f32_16x16x32_bf16 v[72:75], v[164:167], v[212:215], v[72:75]
	v_mfma_f32_16x16x32_bf16 v[124:127], v[160:163], v[192:195], v[124:127]
	v_mfma_f32_16x16x32_bf16 v[120:123], v[168:171], v[192:195], v[120:123]
	v_mfma_f32_16x16x32_bf16 v[108:111], v[160:163], v[200:203], v[108:111]
	v_mfma_f32_16x16x32_bf16 v[104:107], v[168:171], v[200:203], v[104:107]
	v_mfma_f32_16x16x32_bf16 v[92:95], v[160:163], v[208:211], v[92:95]
	v_mfma_f32_16x16x32_bf16 v[88:91], v[168:171], v[208:211], v[88:91]
	v_mfma_f32_16x16x32_bf16 v[76:79], v[160:163], v[216:219], v[76:79]
	v_mfma_f32_16x16x32_bf16 v[72:75], v[168:171], v[216:219], v[72:75]
	s_setprio 0
	s_setprio 1
	v_mfma_f32_16x16x32_bf16 v[116:119], v[172:175], v[188:191], v[116:119]
	v_mfma_f32_16x16x32_bf16 v[112:115], v[180:183], v[188:191], v[112:115]
	v_mfma_f32_16x16x32_bf16 v[100:103], v[172:175], v[196:199], v[100:103]
	v_mfma_f32_16x16x32_bf16 v[96:99], v[180:183], v[196:199], v[96:99]
	v_mfma_f32_16x16x32_bf16 v[84:87], v[172:175], v[204:207], v[84:87]
	v_mfma_f32_16x16x32_bf16 v[80:83], v[180:183], v[204:207], v[80:83]
	v_mfma_f32_16x16x32_bf16 v[68:71], v[172:175], v[212:215], v[68:71]
	v_mfma_f32_16x16x32_bf16 v[64:67], v[180:183], v[212:215], v[64:67]
	v_mfma_f32_16x16x32_bf16 v[116:119], v[176:179], v[192:195], v[116:119]
	v_mfma_f32_16x16x32_bf16 v[112:115], v[184:187], v[192:195], v[112:115]
	v_mfma_f32_16x16x32_bf16 v[100:103], v[176:179], v[200:203], v[100:103]
	v_mfma_f32_16x16x32_bf16 v[96:99], v[184:187], v[200:203], v[96:99]
	s_barrier
	v_mfma_f32_16x16x32_bf16 v[84:87], v[176:179], v[208:211], v[84:87]
	v_mfma_f32_16x16x32_bf16 v[80:83], v[184:187], v[208:211], v[80:83]
	v_mfma_f32_16x16x32_bf16 v[68:71], v[176:179], v[216:219], v[68:71]
	v_mfma_f32_16x16x32_bf16 v[64:67], v[184:187], v[216:219], v[64:67]
	s_setprio 0
	s_add_i32 s28, s52, s34
	v_lshl_add_u64 v[156:157], v[156:157], 0, s[12:13]
	s_mov_b32 m0, s28
	ds_read_b128 v[188:191], v153 offset:49152
	ds_read_b128 v[192:195], v153 offset:50176
	ds_read_b128 v[196:199], v153 offset:51200
	ds_read_b128 v[200:203], v153 offset:52224
	ds_read_b128 v[204:207], v153 offset:53248
	ds_read_b128 v[208:211], v153 offset:54272
	ds_read_b128 v[212:215], v153 offset:55296
	ds_read_b128 v[216:219], v153 offset:56320
	global_load_lds_dwordx4 v[156:157], off
	s_add_i32 m0, s28, 0x2000
	s_add_u32 s26, s26, 0x80080
	v_lshl_add_u64 v[156:157], v[220:221], 0, s[12:13]
	s_addc_u32 s27, s27, 0
	s_add_i32 s28, s53, s34
	global_load_lds_dwordx4 v[156:157], off
	v_lshl_add_u64 v[156:157], s[26:27], 0, v[130:131]
	s_mov_b32 m0, s28
	s_nop 0
	global_load_lds_dwordx4 v[156:157], off
	v_lshl_add_u64 v[156:157], s[26:27], 0, v[134:135]
	s_add_i32 m0, s28, 0x2000
	s_nop 0
	global_load_lds_dwordx4 v[156:157], off
	v_lshl_add_u64 v[156:157], v[222:223], 0, s[12:13]
	s_mov_b32 m0, s41
	s_nop 0
	global_load_lds_dwordx4 v[156:157], off
	v_lshl_add_u64 v[156:157], v[224:225], 0, s[12:13]
	s_mov_b32 m0, s42
	s_nop 0
	global_load_lds_dwordx4 v[156:157], off
	s_waitcnt vmcnt(8)
	s_waitcnt lgkmcnt(0)
	s_barrier
	s_setprio 1
	s_waitcnt lgkmcnt(0)
	v_mfma_f32_16x16x32_bf16 v[60:63], v[144:147], v[188:191], v[60:63]
	v_mfma_f32_16x16x32_bf16 v[56:59], v[164:167], v[188:191], v[56:59]
	v_mfma_f32_16x16x32_bf16 v[44:47], v[144:147], v[196:199], v[44:47]
	v_mfma_f32_16x16x32_bf16 v[40:43], v[164:167], v[196:199], v[40:43]
	v_mfma_f32_16x16x32_bf16 v[28:31], v[144:147], v[204:207], v[28:31]
	v_mfma_f32_16x16x32_bf16 v[24:27], v[164:167], v[204:207], v[24:27]
	v_mfma_f32_16x16x32_bf16 v[12:15], v[144:147], v[212:215], v[12:15]
	v_mfma_f32_16x16x32_bf16 v[8:11], v[164:167], v[212:215], v[8:11]
	v_mfma_f32_16x16x32_bf16 v[60:63], v[160:163], v[192:195], v[60:63]
	v_mfma_f32_16x16x32_bf16 v[56:59], v[168:171], v[192:195], v[56:59]
	v_mfma_f32_16x16x32_bf16 v[44:47], v[160:163], v[200:203], v[44:47]
	v_mfma_f32_16x16x32_bf16 v[40:43], v[168:171], v[200:203], v[40:43]
	v_mfma_f32_16x16x32_bf16 v[28:31], v[160:163], v[208:211], v[28:31]
	v_mfma_f32_16x16x32_bf16 v[24:27], v[168:171], v[208:211], v[24:27]
	v_mfma_f32_16x16x32_bf16 v[12:15], v[160:163], v[216:219], v[12:15]
	v_mfma_f32_16x16x32_bf16 v[8:11], v[168:171], v[216:219], v[8:11]
	s_setprio 0
	s_setprio 1
	v_mfma_f32_16x16x32_bf16 v[52:55], v[172:175], v[188:191], v[52:55]
	v_mfma_f32_16x16x32_bf16 v[48:51], v[180:183], v[188:191], v[48:51]
	v_mfma_f32_16x16x32_bf16 v[36:39], v[172:175], v[196:199], v[36:39]
	v_mfma_f32_16x16x32_bf16 v[32:35], v[180:183], v[196:199], v[32:35]
	v_mfma_f32_16x16x32_bf16 v[20:23], v[172:175], v[204:207], v[20:23]
	v_mfma_f32_16x16x32_bf16 v[16:19], v[180:183], v[204:207], v[16:19]
	v_mfma_f32_16x16x32_bf16 v[4:7], v[172:175], v[212:215], v[4:7]
	v_mfma_f32_16x16x32_bf16 v[0:3], v[180:183], v[212:215], v[0:3]
	v_mfma_f32_16x16x32_bf16 v[52:55], v[176:179], v[192:195], v[52:55]
	v_mfma_f32_16x16x32_bf16 v[48:51], v[184:187], v[192:195], v[48:51]
	v_mfma_f32_16x16x32_bf16 v[36:39], v[176:179], v[200:203], v[36:39]
	v_mfma_f32_16x16x32_bf16 v[32:35], v[184:187], v[200:203], v[32:35]
	s_barrier
	v_mfma_f32_16x16x32_bf16 v[20:23], v[176:179], v[208:211], v[20:23]
	v_mfma_f32_16x16x32_bf16 v[16:19], v[184:187], v[208:211], v[16:19]
	v_mfma_f32_16x16x32_bf16 v[4:7], v[176:179], v[216:219], v[4:7]
	v_mfma_f32_16x16x32_bf16 v[0:3], v[184:187], v[216:219], v[0:3]
	s_setprio 0
	s_add_i32 s51, s51, 2
	s_add_u32 s24, s24, 0x100
	s_addc_u32 s25, s25, 0
	s_add_u32 s23, s23, 0x100
	s_addc_u32 s50, s50, 0
	s_cmp_gt_u32 s51, 29
	s_cbranch_scc0 .LBB0_1079
	s_and_b64 vcc, exec, s[14:15]
	s_cbranch_vccz .LBB0_1082
	s_barrier

.LBB0_1176:
	ds_read_b128 v[152:155], v149
	ds_read_b128 v[160:163], v149 offset:1024
	ds_read_b128 v[164:167], v149 offset:2048
	ds_read_b128 v[168:171], v149 offset:3072
	ds_read_b128 v[172:175], v150
	ds_read_b128 v[176:179], v150 offset:1024
	ds_read_b128 v[180:183], v150 offset:2048
	ds_read_b128 v[184:187], v150 offset:3072
	s_add_u32 s34, s30, 0xfff80080
	s_addc_u32 s35, s31, -1
	s_cmp_eq_u32 s62, 4
	s_cselect_b32 s37, s17, s35
	s_cselect_b32 s36, s19, s34
	s_cselect_b32 s35, s21, s61
	s_cselect_b32 s34, s59, s60
	v_lshl_add_u64 v[144:145], s[30:31], 0, v[136:137]
	s_add_i32 m0, s29, 0xc000
	ds_read_b128 v[188:191], v151
	ds_read_b128 v[192:195], v151 offset:1024
	ds_read_b128 v[196:199], v151 offset:2048
	ds_read_b128 v[200:203], v151 offset:3072
	ds_read_b128 v[204:207], v151 offset:4096
	ds_read_b128 v[208:211], v151 offset:5120
	ds_read_b128 v[212:215], v151 offset:6144
	ds_read_b128 v[216:219], v151 offset:7168
	global_load_lds_dwordx4 v[144:145], off
	v_lshl_add_u64 v[144:145], s[30:31], 0, v[138:139]
	s_add_i32 m0, s29, 0xe000
	s_nop 0
	global_load_lds_dwordx4 v[144:145], off
	s_waitcnt vmcnt(8)
	s_waitcnt lgkmcnt(0)
	s_barrier
	s_setprio 1
	s_waitcnt lgkmcnt(0)
	v_mfma_f32_16x16x32_bf16 v[124:127], v[152:155], v[188:191], v[124:127]
	v_mfma_f32_16x16x32_bf16 v[120:123], v[164:167], v[188:191], v[120:123]
	v_mfma_f32_16x16x32_bf16 v[116:119], v[152:155], v[196:199], v[116:119]
	v_mfma_f32_16x16x32_bf16 v[108:111], v[164:167], v[196:199], v[108:111]
	v_mfma_f32_16x16x32_bf16 v[100:103], v[152:155], v[204:207], v[100:103]
	v_mfma_f32_16x16x32_bf16 v[92:95], v[164:167], v[204:207], v[92:95]
	v_mfma_f32_16x16x32_bf16 v[84:87], v[152:155], v[212:215], v[84:87]
	v_mfma_f32_16x16x32_bf16 v[76:79], v[164:167], v[212:215], v[76:79]
	v_mfma_f32_16x16x32_bf16 v[124:127], v[160:163], v[192:195], v[124:127]
	v_mfma_f32_16x16x32_bf16 v[120:123], v[168:171], v[192:195], v[120:123]
	v_mfma_f32_16x16x32_bf16 v[116:119], v[160:163], v[200:203], v[116:119]
	v_mfma_f32_16x16x32_bf16 v[108:111], v[168:171], v[200:203], v[108:111]
	v_mfma_f32_16x16x32_bf16 v[100:103], v[160:163], v[208:211], v[100:103]
	v_mfma_f32_16x16x32_bf16 v[92:95], v[168:171], v[208:211], v[92:95]
	v_mfma_f32_16x16x32_bf16 v[84:87], v[160:163], v[216:219], v[84:87]
	v_mfma_f32_16x16x32_bf16 v[76:79], v[168:171], v[216:219], v[76:79]
	s_setprio 0
	s_setprio 1
	v_mfma_f32_16x16x32_bf16 v[112:115], v[172:175], v[188:191], v[112:115]
	v_mfma_f32_16x16x32_bf16 v[104:107], v[180:183], v[188:191], v[104:107]
	v_mfma_f32_16x16x32_bf16 v[96:99], v[172:175], v[196:199], v[96:99]
	v_mfma_f32_16x16x32_bf16 v[88:91], v[180:183], v[196:199], v[88:91]
	v_mfma_f32_16x16x32_bf16 v[80:83], v[172:175], v[204:207], v[80:83]
	v_mfma_f32_16x16x32_bf16 v[72:75], v[180:183], v[204:207], v[72:75]
	v_mfma_f32_16x16x32_bf16 v[68:71], v[172:175], v[212:215], v[68:71]
	v_mfma_f32_16x16x32_bf16 v[64:67], v[180:183], v[212:215], v[64:67]
	v_mfma_f32_16x16x32_bf16 v[112:115], v[176:179], v[192:195], v[112:115]
	v_mfma_f32_16x16x32_bf16 v[104:107], v[184:187], v[192:195], v[104:107]
	v_mfma_f32_16x16x32_bf16 v[96:99], v[176:179], v[200:203], v[96:99]
	v_mfma_f32_16x16x32_bf16 v[88:91], v[184:187], v[200:203], v[88:91]
	s_barrier
	v_mfma_f32_16x16x32_bf16 v[80:83], v[176:179], v[208:211], v[80:83]
	v_mfma_f32_16x16x32_bf16 v[72:75], v[184:187], v[208:211], v[72:75]
	v_mfma_f32_16x16x32_bf16 v[68:71], v[176:179], v[216:219], v[68:71]
	v_mfma_f32_16x16x32_bf16 v[64:67], v[184:187], v[216:219], v[64:67]
	s_setprio 0
	s_add_i32 s63, s53, s43
	v_lshl_add_u64 v[144:145], s[34:35], 0, v[130:131]
	s_mov_b32 m0, s63
	ds_read_b128 v[188:191], v151 offset:16384
	ds_read_b128 v[192:195], v151 offset:17408
	ds_read_b128 v[196:199], v151 offset:18432
	ds_read_b128 v[200:203], v151 offset:19456
	ds_read_b128 v[204:207], v151 offset:20480
	ds_read_b128 v[208:211], v151 offset:21504
	ds_read_b128 v[212:215], v151 offset:22528
	ds_read_b128 v[216:219], v151 offset:23552
	global_load_lds_dwordx4 v[144:145], off
	s_add_i32 m0, s63, 0x2000
	s_add_u32 s64, s34, 0x80000
	v_lshl_add_u64 v[156:157], s[34:35], 0, v[134:135]
	s_addc_u32 s65, s35, 0
	s_add_i32 s63, s54, s43
	global_load_lds_dwordx4 v[156:157], off
	v_lshl_add_u64 v[220:221], s[64:65], 0, v[130:131]
	s_mov_b32 m0, s63
	v_lshl_add_u64 v[222:223], s[36:37], 0, v[132:133]
	global_load_lds_dwordx4 v[220:221], off
	v_lshl_add_u64 v[220:221], s[64:65], 0, v[134:135]
	s_add_i32 m0, s63, 0x2000
	s_nop 0
	global_load_lds_dwordx4 v[220:221], off
	v_lshl_add_u64 v[220:221], s[36:37], 0, v[128:129]
	s_mov_b32 m0, s29
	s_nop 0
	global_load_lds_dwordx4 v[220:221], off
	s_mov_b32 m0, s44
	s_nop 0
	global_load_lds_dwordx4 v[222:223], off
	s_waitcnt vmcnt(8)
	s_waitcnt lgkmcnt(0)
	s_barrier
	s_setprio 1
	s_waitcnt lgkmcnt(0)
	v_mfma_f32_16x16x32_bf16 v[60:63], v[152:155], v[188:191], v[60:63]
	v_mfma_f32_16x16x32_bf16 v[56:59], v[164:167], v[188:191], v[56:59]
	v_mfma_f32_16x16x32_bf16 v[52:55], v[152:155], v[196:199], v[52:55]
	v_mfma_f32_16x16x32_bf16 v[44:47], v[164:167], v[196:199], v[44:47]
	v_mfma_f32_16x16x32_bf16 v[36:39], v[152:155], v[204:207], v[36:39]
	v_mfma_f32_16x16x32_bf16 v[28:31], v[164:167], v[204:207], v[28:31]
	v_mfma_f32_16x16x32_bf16 v[20:23], v[152:155], v[212:215], v[20:23]
	v_mfma_f32_16x16x32_bf16 v[12:15], v[164:167], v[212:215], v[12:15]
	v_mfma_f32_16x16x32_bf16 v[60:63], v[160:163], v[192:195], v[60:63]
	v_mfma_f32_16x16x32_bf16 v[56:59], v[168:171], v[192:195], v[56:59]
	v_mfma_f32_16x16x32_bf16 v[52:55], v[160:163], v[200:203], v[52:55]
	v_mfma_f32_16x16x32_bf16 v[44:47], v[168:171], v[200:203], v[44:47]
	v_mfma_f32_16x16x32_bf16 v[36:39], v[160:163], v[208:211], v[36:39]
	v_mfma_f32_16x16x32_bf16 v[28:31], v[168:171], v[208:211], v[28:31]
	v_mfma_f32_16x16x32_bf16 v[20:23], v[160:163], v[216:219], v[20:23]
	v_mfma_f32_16x16x32_bf16 v[12:15], v[168:171], v[216:219], v[12:15]
	s_setprio 0
	s_setprio 1
	v_mfma_f32_16x16x32_bf16 v[48:51], v[172:175], v[188:191], v[48:51]
	v_mfma_f32_16x16x32_bf16 v[40:43], v[180:183], v[188:191], v[40:43]
	v_mfma_f32_16x16x32_bf16 v[32:35], v[172:175], v[196:199], v[32:35]
	v_mfma_f32_16x16x32_bf16 v[24:27], v[180:183], v[196:199], v[24:27]
	v_mfma_f32_16x16x32_bf16 v[16:19], v[172:175], v[204:207], v[16:19]
	v_mfma_f32_16x16x32_bf16 v[8:11], v[180:183], v[204:207], v[8:11]
	v_mfma_f32_16x16x32_bf16 v[4:7], v[172:175], v[212:215], v[4:7]
	v_mfma_f32_16x16x32_bf16 v[0:3], v[180:183], v[212:215], v[0:3]
	v_mfma_f32_16x16x32_bf16 v[48:51], v[176:179], v[192:195], v[48:51]
	v_mfma_f32_16x16x32_bf16 v[40:43], v[184:187], v[192:195], v[40:43]
	v_mfma_f32_16x16x32_bf16 v[32:35], v[176:179], v[200:203], v[32:35]
	v_mfma_f32_16x16x32_bf16 v[24:27], v[184:187], v[200:203], v[24:27]
	s_barrier
	v_mfma_f32_16x16x32_bf16 v[16:19], v[176:179], v[208:211], v[16:19]
	v_mfma_f32_16x16x32_bf16 v[8:11], v[184:187], v[208:211], v[8:11]
	v_mfma_f32_16x16x32_bf16 v[4:7], v[176:179], v[216:219], v[4:7]
	v_mfma_f32_16x16x32_bf16 v[0:3], v[184:187], v[216:219], v[0:3]
	s_setprio 0
	s_add_i32 s63, 0, 0x18000
	s_add_i32 s64, 0, 0x1c000
	v_add_u32_e32 v168, s63, v147
	v_add_u32_e32 v184, s64, v147
	ds_read_b128 v[152:155], v168
	ds_read_b128 v[160:163], v168 offset:1024
	ds_read_b128 v[164:167], v168 offset:2048
	ds_read_b128 v[168:171], v168 offset:3072
	ds_read_b128 v[172:175], v184
	ds_read_b128 v[176:179], v184 offset:1024
	ds_read_b128 v[180:183], v184 offset:2048
	ds_read_b128 v[184:187], v184 offset:3072
	s_add_u32 s36, s36, 0x80000
	s_addc_u32 s37, s37, 0
	s_mov_b32 m0, s45
	v_lshl_add_u64 v[224:225], s[36:37], 0, v[128:129]
	ds_read_b128 v[188:191], v151 offset:32768
	ds_read_b128 v[192:195], v151 offset:33792
	ds_read_b128 v[196:199], v151 offset:34816
	ds_read_b128 v[200:203], v151 offset:35840
	ds_read_b128 v[204:207], v151 offset:36864
	ds_read_b128 v[208:211], v151 offset:37888
	ds_read_b128 v[212:215], v151 offset:38912
	ds_read_b128 v[216:219], v151 offset:39936
	global_load_lds_dwordx4 v[224:225], off
	v_lshl_add_u64 v[224:225], s[36:37], 0, v[132:133]
	s_mov_b32 m0, s46
	s_nop 0
	global_load_lds_dwordx4 v[224:225], off
	s_waitcnt vmcnt(8)
	s_waitcnt lgkmcnt(0)
	s_barrier
	s_setprio 1
	s_waitcnt lgkmcnt(0)
	v_mfma_f32_16x16x32_bf16 v[124:127], v[152:155], v[188:191], v[124:127]
	v_mfma_f32_16x16x32_bf16 v[120:123], v[164:167], v[188:191], v[120:123]
	v_mfma_f32_16x16x32_bf16 v[116:119], v[152:155], v[196:199], v[116:119]
	v_mfma_f32_16x16x32_bf16 v[108:111], v[164:167], v[196:199], v[108:111]
	v_mfma_f32_16x16x32_bf16 v[100:103], v[152:155], v[204:207], v[100:103]
	v_mfma_f32_16x16x32_bf16 v[92:95], v[164:167], v[204:207], v[92:95]
	v_mfma_f32_16x16x32_bf16 v[84:87], v[152:155], v[212:215], v[84:87]
	v_mfma_f32_16x16x32_bf16 v[76:79], v[164:167], v[212:215], v[76:79]
	v_mfma_f32_16x16x32_bf16 v[124:127], v[160:163], v[192:195], v[124:127]
	v_mfma_f32_16x16x32_bf16 v[120:123], v[168:171], v[192:195], v[120:123]
	v_mfma_f32_16x16x32_bf16 v[116:119], v[160:163], v[200:203], v[116:119]
	v_mfma_f32_16x16x32_bf16 v[108:111], v[168:171], v[200:203], v[108:111]
	v_mfma_f32_16x16x32_bf16 v[100:103], v[160:163], v[208:211], v[100:103]
	v_mfma_f32_16x16x32_bf16 v[92:95], v[168:171], v[208:211], v[92:95]
	v_mfma_f32_16x16x32_bf16 v[84:87], v[160:163], v[216:219], v[84:87]
	v_mfma_f32_16x16x32_bf16 v[76:79], v[168:171], v[216:219], v[76:79]
	s_setprio 0
	s_setprio 1
	v_mfma_f32_16x16x32_bf16 v[112:115], v[172:175], v[188:191], v[112:115]
	v_mfma_f32_16x16x32_bf16 v[104:107], v[180:183], v[188:191], v[104:107]
	v_mfma_f32_16x16x32_bf16 v[96:99], v[172:175], v[196:199], v[96:99]
	v_mfma_f32_16x16x32_bf16 v[88:91], v[180:183], v[196:199], v[88:91]
	v_mfma_f32_16x16x32_bf16 v[80:83], v[172:175], v[204:207], v[80:83]
	v_mfma_f32_16x16x32_bf16 v[72:75], v[180:183], v[204:207], v[72:75]
	v_mfma_f32_16x16x32_bf16 v[68:71], v[172:175], v[212:215], v[68:71]
	v_mfma_f32_16x16x32_bf16 v[64:67], v[180:183], v[212:215], v[64:67]
	v_mfma_f32_16x16x32_bf16 v[112:115], v[176:179], v[192:195], v[112:115]
	v_mfma_f32_16x16x32_bf16 v[104:107], v[184:187], v[192:195], v[104:107]
	v_mfma_f32_16x16x32_bf16 v[96:99], v[176:179], v[200:203], v[96:99]
	v_mfma_f32_16x16x32_bf16 v[88:91], v[184:187], v[200:203], v[88:91]
	s_barrier
	v_mfma_f32_16x16x32_bf16 v[80:83], v[176:179], v[208:211], v[80:83]
	v_mfma_f32_16x16x32_bf16 v[72:75], v[184:187], v[208:211], v[72:75]
	v_mfma_f32_16x16x32_bf16 v[68:71], v[176:179], v[216:219], v[68:71]
	v_mfma_f32_16x16x32_bf16 v[64:67], v[184:187], v[216:219], v[64:67]
	s_setprio 0
	s_add_i32 s36, s63, s43
	v_lshl_add_u64 v[144:145], v[144:145], 0, s[4:5]
	s_mov_b32 m0, s36
	ds_read_b128 v[188:191], v151 offset:49152
	ds_read_b128 v[192:195], v151 offset:50176
	ds_read_b128 v[196:199], v151 offset:51200
	ds_read_b128 v[200:203], v151 offset:52224
	ds_read_b128 v[204:207], v151 offset:53248
	ds_read_b128 v[208:211], v151 offset:54272
	ds_read_b128 v[212:215], v151 offset:55296
	ds_read_b128 v[216:219], v151 offset:56320
	global_load_lds_dwordx4 v[144:145], off
	s_add_i32 m0, s36, 0x2000
	s_add_u32 s34, s34, 0x80080
	v_lshl_add_u64 v[144:145], v[156:157], 0, s[4:5]
	s_addc_u32 s35, s35, 0
	s_add_i32 s36, s64, s43
	global_load_lds_dwordx4 v[144:145], off
	v_lshl_add_u64 v[144:145], s[34:35], 0, v[130:131]
	s_mov_b32 m0, s36
	s_nop 0
	global_load_lds_dwordx4 v[144:145], off
	v_lshl_add_u64 v[144:145], s[34:35], 0, v[134:135]
	s_add_i32 m0, s36, 0x2000
	s_nop 0
	global_load_lds_dwordx4 v[144:145], off
	v_lshl_add_u64 v[144:145], v[220:221], 0, s[4:5]
	s_mov_b32 m0, s50
	s_nop 0
	global_load_lds_dwordx4 v[144:145], off
	v_lshl_add_u64 v[144:145], v[222:223], 0, s[4:5]
	s_mov_b32 m0, s51
	s_nop 0
	global_load_lds_dwordx4 v[144:145], off
	s_waitcnt vmcnt(8)
	s_waitcnt lgkmcnt(0)
	s_barrier
	s_setprio 1
	s_waitcnt lgkmcnt(0)
	v_mfma_f32_16x16x32_bf16 v[60:63], v[152:155], v[188:191], v[60:63]
	v_mfma_f32_16x16x32_bf16 v[56:59], v[164:167], v[188:191], v[56:59]
	v_mfma_f32_16x16x32_bf16 v[52:55], v[152:155], v[196:199], v[52:55]
	v_mfma_f32_16x16x32_bf16 v[44:47], v[164:167], v[196:199], v[44:47]
	v_mfma_f32_16x16x32_bf16 v[36:39], v[152:155], v[204:207], v[36:39]
	v_mfma_f32_16x16x32_bf16 v[28:31], v[164:167], v[204:207], v[28:31]
	v_mfma_f32_16x16x32_bf16 v[20:23], v[152:155], v[212:215], v[20:23]
	v_mfma_f32_16x16x32_bf16 v[12:15], v[164:167], v[212:215], v[12:15]
	v_mfma_f32_16x16x32_bf16 v[60:63], v[160:163], v[192:195], v[60:63]
	v_mfma_f32_16x16x32_bf16 v[56:59], v[168:171], v[192:195], v[56:59]
	v_mfma_f32_16x16x32_bf16 v[52:55], v[160:163], v[200:203], v[52:55]
	v_mfma_f32_16x16x32_bf16 v[44:47], v[168:171], v[200:203], v[44:47]
	v_mfma_f32_16x16x32_bf16 v[36:39], v[160:163], v[208:211], v[36:39]
	v_mfma_f32_16x16x32_bf16 v[28:31], v[168:171], v[208:211], v[28:31]
	v_mfma_f32_16x16x32_bf16 v[20:23], v[160:163], v[216:219], v[20:23]
	v_mfma_f32_16x16x32_bf16 v[12:15], v[168:171], v[216:219], v[12:15]
	s_setprio 0
	s_setprio 1
	v_mfma_f32_16x16x32_bf16 v[48:51], v[172:175], v[188:191], v[48:51]
	v_mfma_f32_16x16x32_bf16 v[40:43], v[180:183], v[188:191], v[40:43]
	v_mfma_f32_16x16x32_bf16 v[32:35], v[172:175], v[196:199], v[32:35]
	v_mfma_f32_16x16x32_bf16 v[24:27], v[180:183], v[196:199], v[24:27]
	v_mfma_f32_16x16x32_bf16 v[16:19], v[172:175], v[204:207], v[16:19]
	v_mfma_f32_16x16x32_bf16 v[8:11], v[180:183], v[204:207], v[8:11]
	v_mfma_f32_16x16x32_bf16 v[4:7], v[172:175], v[212:215], v[4:7]
	v_mfma_f32_16x16x32_bf16 v[0:3], v[180:183], v[212:215], v[0:3]
	v_mfma_f32_16x16x32_bf16 v[48:51], v[176:179], v[192:195], v[48:51]
	v_mfma_f32_16x16x32_bf16 v[40:43], v[184:187], v[192:195], v[40:43]
	v_mfma_f32_16x16x32_bf16 v[32:35], v[176:179], v[200:203], v[32:35]
	v_mfma_f32_16x16x32_bf16 v[24:27], v[184:187], v[200:203], v[24:27]
	s_barrier
	v_mfma_f32_16x16x32_bf16 v[16:19], v[176:179], v[208:211], v[16:19]
	v_mfma_f32_16x16x32_bf16 v[8:11], v[184:187], v[208:211], v[8:11]
	v_mfma_f32_16x16x32_bf16 v[4:7], v[176:179], v[216:219], v[4:7]
	v_mfma_f32_16x16x32_bf16 v[0:3], v[184:187], v[216:219], v[0:3]
	s_setprio 0
	s_add_i32 s62, s62, 2
	s_add_u32 s30, s30, 0x100
	s_addc_u32 s31, s31, 0
	s_add_u32 s60, s60, 0x100
	s_addc_u32 s61, s61, 0
	s_cmp_gt_u32 s62, 5
	s_cbranch_scc0 .LBB0_1176
	s_and_b64 vcc, exec, s[6:7]
	s_cbranch_vccz .LBB0_1179
	s_barrier

.LBB0_1331:
	ds_read_b128 v[140:143], v147
	ds_read_b128 v[152:155], v147 offset:1024
	ds_read_b128 v[160:163], v147 offset:2048
	ds_read_b128 v[164:167], v147 offset:3072
	ds_read_b128 v[168:171], v148
	ds_read_b128 v[172:175], v148 offset:1024
	ds_read_b128 v[176:179], v148 offset:2048
	ds_read_b128 v[180:183], v148 offset:3072
	s_add_u32 s34, s30, 0xfffe0080
	s_addc_u32 s35, s31, -1
	s_cmp_eq_u32 s55, 4
	s_cselect_b32 s37, s17, s35
	s_cselect_b32 s36, s19, s34
	s_cselect_b32 s35, s21, s54
	s_cselect_b32 s34, s27, s53
	v_lshl_add_u64 v[156:157], s[30:31], 0, v[132:133]
	s_add_i32 m0, s29, 0xc000
	ds_read_b128 v[184:187], v149
	ds_read_b128 v[188:191], v149 offset:1024
	ds_read_b128 v[192:195], v149 offset:2048
	ds_read_b128 v[196:199], v149 offset:3072
	ds_read_b128 v[200:203], v149 offset:4096
	ds_read_b128 v[204:207], v149 offset:5120
	ds_read_b128 v[208:211], v149 offset:6144
	ds_read_b128 v[212:215], v149 offset:7168
	global_load_lds_dwordx4 v[156:157], off
	v_lshl_add_u64 v[156:157], s[30:31], 0, v[134:135]
	s_add_i32 m0, s29, 0xe000
	s_nop 0
	global_load_lds_dwordx4 v[156:157], off
	s_waitcnt vmcnt(8)
	s_waitcnt lgkmcnt(0)
	s_barrier
	s_setprio 1
	s_waitcnt lgkmcnt(0)
	v_mfma_f32_16x16x32_bf16 v[124:127], v[140:143], v[184:187], v[124:127]
	v_mfma_f32_16x16x32_bf16 v[120:123], v[160:163], v[184:187], v[120:123]
	v_mfma_f32_16x16x32_bf16 v[108:111], v[140:143], v[192:195], v[108:111]
	v_mfma_f32_16x16x32_bf16 v[104:107], v[160:163], v[192:195], v[104:107]
	v_mfma_f32_16x16x32_bf16 v[92:95], v[140:143], v[200:203], v[92:95]
	v_mfma_f32_16x16x32_bf16 v[88:91], v[160:163], v[200:203], v[88:91]
	v_mfma_f32_16x16x32_bf16 v[76:79], v[140:143], v[208:211], v[76:79]
	v_mfma_f32_16x16x32_bf16 v[72:75], v[160:163], v[208:211], v[72:75]
	v_mfma_f32_16x16x32_bf16 v[124:127], v[152:155], v[188:191], v[124:127]
	v_mfma_f32_16x16x32_bf16 v[120:123], v[164:167], v[188:191], v[120:123]
	v_mfma_f32_16x16x32_bf16 v[108:111], v[152:155], v[196:199], v[108:111]
	v_mfma_f32_16x16x32_bf16 v[104:107], v[164:167], v[196:199], v[104:107]
	v_mfma_f32_16x16x32_bf16 v[92:95], v[152:155], v[204:207], v[92:95]
	v_mfma_f32_16x16x32_bf16 v[88:91], v[164:167], v[204:207], v[88:91]
	v_mfma_f32_16x16x32_bf16 v[76:79], v[152:155], v[212:215], v[76:79]
	v_mfma_f32_16x16x32_bf16 v[72:75], v[164:167], v[212:215], v[72:75]
	s_setprio 0
	s_setprio 1
	v_mfma_f32_16x16x32_bf16 v[116:119], v[168:171], v[184:187], v[116:119]
	v_mfma_f32_16x16x32_bf16 v[112:115], v[176:179], v[184:187], v[112:115]
	v_mfma_f32_16x16x32_bf16 v[100:103], v[168:171], v[192:195], v[100:103]
	v_mfma_f32_16x16x32_bf16 v[96:99], v[176:179], v[192:195], v[96:99]
	v_mfma_f32_16x16x32_bf16 v[84:87], v[168:171], v[200:203], v[84:87]
	v_mfma_f32_16x16x32_bf16 v[80:83], v[176:179], v[200:203], v[80:83]
	v_mfma_f32_16x16x32_bf16 v[68:71], v[168:171], v[208:211], v[68:71]
	v_mfma_f32_16x16x32_bf16 v[64:67], v[176:179], v[208:211], v[64:67]
	v_mfma_f32_16x16x32_bf16 v[116:119], v[172:175], v[188:191], v[116:119]
	v_mfma_f32_16x16x32_bf16 v[112:115], v[180:183], v[188:191], v[112:115]
	v_mfma_f32_16x16x32_bf16 v[100:103], v[172:175], v[196:199], v[100:103]
	v_mfma_f32_16x16x32_bf16 v[96:99], v[180:183], v[196:199], v[96:99]
	s_barrier
	v_mfma_f32_16x16x32_bf16 v[84:87], v[172:175], v[204:207], v[84:87]
	v_mfma_f32_16x16x32_bf16 v[80:83], v[180:183], v[204:207], v[80:83]
	v_mfma_f32_16x16x32_bf16 v[68:71], v[172:175], v[212:215], v[68:71]
	v_mfma_f32_16x16x32_bf16 v[64:67], v[180:183], v[212:215], v[64:67]
	s_setprio 0
	s_add_i32 s56, s51, s42
	v_lshl_add_u64 v[156:157], s[34:35], 0, v[128:129]
	s_mov_b32 m0, s56
	ds_read_b128 v[184:187], v149 offset:16384
	ds_read_b128 v[188:191], v149 offset:17408
	ds_read_b128 v[192:195], v149 offset:18432
	ds_read_b128 v[196:199], v149 offset:19456
	ds_read_b128 v[200:203], v149 offset:20480
	ds_read_b128 v[204:207], v149 offset:21504
	ds_read_b128 v[208:211], v149 offset:22528
	ds_read_b128 v[212:215], v149 offset:23552
	global_load_lds_dwordx4 v[156:157], off
	s_add_i32 m0, s56, 0x2000
	s_add_u32 s56, s34, 0x20000
	v_lshl_add_u64 v[216:217], s[34:35], 0, v[130:131]
	s_addc_u32 s57, s35, 0
	s_add_i32 s58, s52, s42
	global_load_lds_dwordx4 v[216:217], off
	v_lshl_add_u64 v[218:219], s[56:57], 0, v[128:129]
	s_mov_b32 m0, s58
	v_lshl_add_u64 v[220:221], s[36:37], 0, v[130:131]
	global_load_lds_dwordx4 v[218:219], off
	v_lshl_add_u64 v[218:219], s[56:57], 0, v[130:131]
	s_add_i32 m0, s58, 0x2000
	s_nop 0
	global_load_lds_dwordx4 v[218:219], off
	v_lshl_add_u64 v[218:219], s[36:37], 0, v[128:129]
	s_mov_b32 m0, s29
	s_nop 0
	global_load_lds_dwordx4 v[218:219], off
	s_mov_b32 m0, s43
	s_nop 0
	global_load_lds_dwordx4 v[220:221], off
	s_waitcnt vmcnt(8)
	s_waitcnt lgkmcnt(0)
	s_barrier
	s_setprio 1
	s_waitcnt lgkmcnt(0)
	v_mfma_f32_16x16x32_bf16 v[60:63], v[140:143], v[184:187], v[60:63]
	v_mfma_f32_16x16x32_bf16 v[56:59], v[160:163], v[184:187], v[56:59]
	v_mfma_f32_16x16x32_bf16 v[44:47], v[140:143], v[192:195], v[44:47]
	v_mfma_f32_16x16x32_bf16 v[40:43], v[160:163], v[192:195], v[40:43]
	v_mfma_f32_16x16x32_bf16 v[28:31], v[140:143], v[200:203], v[28:31]
	v_mfma_f32_16x16x32_bf16 v[24:27], v[160:163], v[200:203], v[24:27]
	v_mfma_f32_16x16x32_bf16 v[12:15], v[140:143], v[208:211], v[12:15]
	v_mfma_f32_16x16x32_bf16 v[8:11], v[160:163], v[208:211], v[8:11]
	v_mfma_f32_16x16x32_bf16 v[60:63], v[152:155], v[188:191], v[60:63]
	v_mfma_f32_16x16x32_bf16 v[56:59], v[164:167], v[188:191], v[56:59]
	v_mfma_f32_16x16x32_bf16 v[44:47], v[152:155], v[196:199], v[44:47]
	v_mfma_f32_16x16x32_bf16 v[40:43], v[164:167], v[196:199], v[40:43]
	v_mfma_f32_16x16x32_bf16 v[28:31], v[152:155], v[204:207], v[28:31]
	v_mfma_f32_16x16x32_bf16 v[24:27], v[164:167], v[204:207], v[24:27]
	v_mfma_f32_16x16x32_bf16 v[12:15], v[152:155], v[212:215], v[12:15]
	v_mfma_f32_16x16x32_bf16 v[8:11], v[164:167], v[212:215], v[8:11]
	s_setprio 0
	s_setprio 1
	v_mfma_f32_16x16x32_bf16 v[52:55], v[168:171], v[184:187], v[52:55]
	v_mfma_f32_16x16x32_bf16 v[48:51], v[176:179], v[184:187], v[48:51]
	v_mfma_f32_16x16x32_bf16 v[36:39], v[168:171], v[192:195], v[36:39]
	v_mfma_f32_16x16x32_bf16 v[32:35], v[176:179], v[192:195], v[32:35]
	v_mfma_f32_16x16x32_bf16 v[20:23], v[168:171], v[200:203], v[20:23]
	v_mfma_f32_16x16x32_bf16 v[16:19], v[176:179], v[200:203], v[16:19]
	v_mfma_f32_16x16x32_bf16 v[4:7], v[168:171], v[208:211], v[4:7]
	v_mfma_f32_16x16x32_bf16 v[0:3], v[176:179], v[208:211], v[0:3]
	v_mfma_f32_16x16x32_bf16 v[52:55], v[172:175], v[188:191], v[52:55]
	v_mfma_f32_16x16x32_bf16 v[48:51], v[180:183], v[188:191], v[48:51]
	v_mfma_f32_16x16x32_bf16 v[36:39], v[172:175], v[196:199], v[36:39]
	v_mfma_f32_16x16x32_bf16 v[32:35], v[180:183], v[196:199], v[32:35]
	s_barrier
	v_mfma_f32_16x16x32_bf16 v[20:23], v[172:175], v[204:207], v[20:23]
	v_mfma_f32_16x16x32_bf16 v[16:19], v[180:183], v[204:207], v[16:19]
	v_mfma_f32_16x16x32_bf16 v[4:7], v[172:175], v[212:215], v[4:7]
	v_mfma_f32_16x16x32_bf16 v[0:3], v[180:183], v[212:215], v[0:3]
	s_setprio 0
	s_add_i32 s56, 0, 0x18000
	v_add_u32_e32 v151, s56, v145
	s_add_i32 s57, 0, 0x1c000
	ds_read_b128 v[140:143], v151
	ds_read_b128 v[152:155], v151 offset:1024
	ds_read_b128 v[160:163], v151 offset:2048
	ds_read_b128 v[164:167], v151 offset:3072
	v_add_u32_e32 v151, s57, v145
	ds_read_b128 v[168:171], v151
	ds_read_b128 v[172:175], v151 offset:1024
	ds_read_b128 v[176:179], v151 offset:2048
	ds_read_b128 v[180:183], v151 offset:3072
	s_add_u32 s36, s36, 0x20000
	s_addc_u32 s37, s37, 0
	s_mov_b32 m0, s44
	v_lshl_add_u64 v[222:223], s[36:37], 0, v[128:129]
	ds_read_b128 v[184:187], v149 offset:32768
	ds_read_b128 v[188:191], v149 offset:33792
	ds_read_b128 v[192:195], v149 offset:34816
	ds_read_b128 v[196:199], v149 offset:35840
	ds_read_b128 v[200:203], v149 offset:36864
	ds_read_b128 v[204:207], v149 offset:37888
	ds_read_b128 v[208:211], v149 offset:38912
	ds_read_b128 v[212:215], v149 offset:39936
	global_load_lds_dwordx4 v[222:223], off
	v_lshl_add_u64 v[222:223], s[36:37], 0, v[130:131]
	s_mov_b32 m0, s45
	s_nop 0
	global_load_lds_dwordx4 v[222:223], off
	s_waitcnt vmcnt(8)
	s_waitcnt lgkmcnt(0)
	s_barrier
	s_setprio 1
	s_waitcnt lgkmcnt(0)
	v_mfma_f32_16x16x32_bf16 v[124:127], v[140:143], v[184:187], v[124:127]
	v_mfma_f32_16x16x32_bf16 v[120:123], v[160:163], v[184:187], v[120:123]
	v_mfma_f32_16x16x32_bf16 v[108:111], v[140:143], v[192:195], v[108:111]
	v_mfma_f32_16x16x32_bf16 v[104:107], v[160:163], v[192:195], v[104:107]
	v_mfma_f32_16x16x32_bf16 v[92:95], v[140:143], v[200:203], v[92:95]
	v_mfma_f32_16x16x32_bf16 v[88:91], v[160:163], v[200:203], v[88:91]
	v_mfma_f32_16x16x32_bf16 v[76:79], v[140:143], v[208:211], v[76:79]
	v_mfma_f32_16x16x32_bf16 v[72:75], v[160:163], v[208:211], v[72:75]
	v_mfma_f32_16x16x32_bf16 v[124:127], v[152:155], v[188:191], v[124:127]
	v_mfma_f32_16x16x32_bf16 v[120:123], v[164:167], v[188:191], v[120:123]
	v_mfma_f32_16x16x32_bf16 v[108:111], v[152:155], v[196:199], v[108:111]
	v_mfma_f32_16x16x32_bf16 v[104:107], v[164:167], v[196:199], v[104:107]
	v_mfma_f32_16x16x32_bf16 v[92:95], v[152:155], v[204:207], v[92:95]
	v_mfma_f32_16x16x32_bf16 v[88:91], v[164:167], v[204:207], v[88:91]
	v_mfma_f32_16x16x32_bf16 v[76:79], v[152:155], v[212:215], v[76:79]
	v_mfma_f32_16x16x32_bf16 v[72:75], v[164:167], v[212:215], v[72:75]
	s_setprio 0
	s_setprio 1
	v_mfma_f32_16x16x32_bf16 v[116:119], v[168:171], v[184:187], v[116:119]
	v_mfma_f32_16x16x32_bf16 v[112:115], v[176:179], v[184:187], v[112:115]
	v_mfma_f32_16x16x32_bf16 v[100:103], v[168:171], v[192:195], v[100:103]
	v_mfma_f32_16x16x32_bf16 v[96:99], v[176:179], v[192:195], v[96:99]
	v_mfma_f32_16x16x32_bf16 v[84:87], v[168:171], v[200:203], v[84:87]
	v_mfma_f32_16x16x32_bf16 v[80:83], v[176:179], v[200:203], v[80:83]
	v_mfma_f32_16x16x32_bf16 v[68:71], v[168:171], v[208:211], v[68:71]
	v_mfma_f32_16x16x32_bf16 v[64:67], v[176:179], v[208:211], v[64:67]
	v_mfma_f32_16x16x32_bf16 v[116:119], v[172:175], v[188:191], v[116:119]
	v_mfma_f32_16x16x32_bf16 v[112:115], v[180:183], v[188:191], v[112:115]
	v_mfma_f32_16x16x32_bf16 v[100:103], v[172:175], v[196:199], v[100:103]
	v_mfma_f32_16x16x32_bf16 v[96:99], v[180:183], v[196:199], v[96:99]
	s_barrier
	v_mfma_f32_16x16x32_bf16 v[84:87], v[172:175], v[204:207], v[84:87]
	v_mfma_f32_16x16x32_bf16 v[80:83], v[180:183], v[204:207], v[80:83]
	v_mfma_f32_16x16x32_bf16 v[68:71], v[172:175], v[212:215], v[68:71]
	v_mfma_f32_16x16x32_bf16 v[64:67], v[180:183], v[212:215], v[64:67]
	s_setprio 0
	s_add_i32 s36, s56, s42
	v_lshl_add_u64 v[156:157], v[156:157], 0, s[12:13]
	s_mov_b32 m0, s36
	ds_read_b128 v[184:187], v149 offset:49152
	ds_read_b128 v[188:191], v149 offset:50176
	ds_read_b128 v[192:195], v149 offset:51200
	ds_read_b128 v[196:199], v149 offset:52224
	ds_read_b128 v[200:203], v149 offset:53248
	ds_read_b128 v[204:207], v149 offset:54272
	ds_read_b128 v[208:211], v149 offset:55296
	ds_read_b128 v[212:215], v149 offset:56320
	global_load_lds_dwordx4 v[156:157], off
	s_add_i32 m0, s36, 0x2000
	s_add_u32 s34, s34, 0x20080
	v_lshl_add_u64 v[156:157], v[216:217], 0, s[12:13]
	s_addc_u32 s35, s35, 0
	s_add_i32 s36, s57, s42
	global_load_lds_dwordx4 v[156:157], off
	v_lshl_add_u64 v[156:157], s[34:35], 0, v[128:129]
	s_mov_b32 m0, s36
	s_nop 0
	global_load_lds_dwordx4 v[156:157], off
	v_lshl_add_u64 v[156:157], s[34:35], 0, v[130:131]
	s_add_i32 m0, s36, 0x2000
	s_nop 0
	global_load_lds_dwordx4 v[156:157], off
	v_lshl_add_u64 v[156:157], v[218:219], 0, s[12:13]
	s_mov_b32 m0, s48
	s_nop 0
	global_load_lds_dwordx4 v[156:157], off
	v_lshl_add_u64 v[156:157], v[220:221], 0, s[12:13]
	s_mov_b32 m0, s49
	s_nop 0
	global_load_lds_dwordx4 v[156:157], off
	s_waitcnt vmcnt(8)
	s_waitcnt lgkmcnt(0)
	s_barrier
	s_setprio 1
	s_waitcnt lgkmcnt(0)
	v_mfma_f32_16x16x32_bf16 v[60:63], v[140:143], v[184:187], v[60:63]
	v_mfma_f32_16x16x32_bf16 v[56:59], v[160:163], v[184:187], v[56:59]
	v_mfma_f32_16x16x32_bf16 v[44:47], v[140:143], v[192:195], v[44:47]
	v_mfma_f32_16x16x32_bf16 v[40:43], v[160:163], v[192:195], v[40:43]
	v_mfma_f32_16x16x32_bf16 v[28:31], v[140:143], v[200:203], v[28:31]
	v_mfma_f32_16x16x32_bf16 v[24:27], v[160:163], v[200:203], v[24:27]
	v_mfma_f32_16x16x32_bf16 v[12:15], v[140:143], v[208:211], v[12:15]
	v_mfma_f32_16x16x32_bf16 v[8:11], v[160:163], v[208:211], v[8:11]
	v_mfma_f32_16x16x32_bf16 v[60:63], v[152:155], v[188:191], v[60:63]
	v_mfma_f32_16x16x32_bf16 v[56:59], v[164:167], v[188:191], v[56:59]
	v_mfma_f32_16x16x32_bf16 v[44:47], v[152:155], v[196:199], v[44:47]
	v_mfma_f32_16x16x32_bf16 v[40:43], v[164:167], v[196:199], v[40:43]
	v_mfma_f32_16x16x32_bf16 v[28:31], v[152:155], v[204:207], v[28:31]
	v_mfma_f32_16x16x32_bf16 v[24:27], v[164:167], v[204:207], v[24:27]
	v_mfma_f32_16x16x32_bf16 v[12:15], v[152:155], v[212:215], v[12:15]
	v_mfma_f32_16x16x32_bf16 v[8:11], v[164:167], v[212:215], v[8:11]
	s_setprio 0
	s_setprio 1
	v_mfma_f32_16x16x32_bf16 v[52:55], v[168:171], v[184:187], v[52:55]
	v_mfma_f32_16x16x32_bf16 v[48:51], v[176:179], v[184:187], v[48:51]
	v_mfma_f32_16x16x32_bf16 v[36:39], v[168:171], v[192:195], v[36:39]
	v_mfma_f32_16x16x32_bf16 v[32:35], v[176:179], v[192:195], v[32:35]
	v_mfma_f32_16x16x32_bf16 v[20:23], v[168:171], v[200:203], v[20:23]
	v_mfma_f32_16x16x32_bf16 v[16:19], v[176:179], v[200:203], v[16:19]
	v_mfma_f32_16x16x32_bf16 v[4:7], v[168:171], v[208:211], v[4:7]
	v_mfma_f32_16x16x32_bf16 v[0:3], v[176:179], v[208:211], v[0:3]
	v_mfma_f32_16x16x32_bf16 v[52:55], v[172:175], v[188:191], v[52:55]
	v_mfma_f32_16x16x32_bf16 v[48:51], v[180:183], v[188:191], v[48:51]
	v_mfma_f32_16x16x32_bf16 v[36:39], v[172:175], v[196:199], v[36:39]
	v_mfma_f32_16x16x32_bf16 v[32:35], v[180:183], v[196:199], v[32:35]
	s_barrier
	v_mfma_f32_16x16x32_bf16 v[20:23], v[172:175], v[204:207], v[20:23]
	v_mfma_f32_16x16x32_bf16 v[16:19], v[180:183], v[204:207], v[16:19]
	v_mfma_f32_16x16x32_bf16 v[4:7], v[172:175], v[212:215], v[4:7]
	v_mfma_f32_16x16x32_bf16 v[0:3], v[180:183], v[212:215], v[0:3]
	s_setprio 0
	s_add_i32 s55, s55, 2
	s_add_u32 s30, s30, 0x100
	s_addc_u32 s31, s31, 0
	s_add_u32 s53, s53, 0x100
	s_addc_u32 s54, s54, 0
	s_cmp_gt_u32 s55, 5
	s_cbranch_scc0 .LBB0_1331
	s_and_b64 vcc, exec, s[14:15]
	s_cbranch_vccz .LBB0_1334
	s_barrier

.LBB0_1426:
	ds_read_b128 v[144:147], v155
	ds_read_b128 v[148:151], v155 offset:1024
	ds_read_b128 v[160:163], v155 offset:2048
	ds_read_b128 v[164:167], v155 offset:3072
	ds_read_b128 v[168:171], v156
	ds_read_b128 v[172:175], v156 offset:1024
	ds_read_b128 v[176:179], v156 offset:2048
	ds_read_b128 v[180:183], v156 offset:3072
	s_add_u32 s36, s34, 0xfff80080
	s_addc_u32 s37, s35, -1
	s_cmp_eq_u32 s64, 28
	s_cselect_b32 s39, s23, s37
	s_cselect_b32 s38, s25, s36
	s_cselect_b32 s37, s27, s63
	s_cselect_b32 s36, s61, s62
	v_lshl_add_u64 v[216:217], s[34:35], 0, v[136:137]
	s_add_i32 m0, s46, 0xc000
	ds_read_b128 v[184:187], v157
	ds_read_b128 v[188:191], v157 offset:1024
	ds_read_b128 v[192:195], v157 offset:2048
	ds_read_b128 v[196:199], v157 offset:3072
	ds_read_b128 v[200:203], v157 offset:4096
	ds_read_b128 v[204:207], v157 offset:5120
	ds_read_b128 v[208:211], v157 offset:6144
	ds_read_b128 v[212:215], v157 offset:7168
	global_load_lds_dwordx4 v[216:217], off
	v_lshl_add_u64 v[216:217], s[34:35], 0, v[138:139]
	s_add_i32 m0, s46, 0xe000
	s_nop 0
	global_load_lds_dwordx4 v[216:217], off
	s_waitcnt vmcnt(8)
	s_waitcnt lgkmcnt(0)
	s_barrier
	s_setprio 1
	s_waitcnt lgkmcnt(0)
	v_mfma_f32_16x16x32_bf16 v[124:127], v[144:147], v[184:187], v[124:127]
	v_mfma_f32_16x16x32_bf16 v[120:123], v[160:163], v[184:187], v[120:123]
	v_mfma_f32_16x16x32_bf16 v[108:111], v[144:147], v[192:195], v[108:111]
	v_mfma_f32_16x16x32_bf16 v[104:107], v[160:163], v[192:195], v[104:107]
	v_mfma_f32_16x16x32_bf16 v[92:95], v[144:147], v[200:203], v[92:95]
	v_mfma_f32_16x16x32_bf16 v[88:91], v[160:163], v[200:203], v[88:91]
	v_mfma_f32_16x16x32_bf16 v[76:79], v[144:147], v[208:211], v[76:79]
	v_mfma_f32_16x16x32_bf16 v[72:75], v[160:163], v[208:211], v[72:75]
	v_mfma_f32_16x16x32_bf16 v[124:127], v[148:151], v[188:191], v[124:127]
	v_mfma_f32_16x16x32_bf16 v[120:123], v[164:167], v[188:191], v[120:123]
	v_mfma_f32_16x16x32_bf16 v[108:111], v[148:151], v[196:199], v[108:111]
	v_mfma_f32_16x16x32_bf16 v[104:107], v[164:167], v[196:199], v[104:107]
	v_mfma_f32_16x16x32_bf16 v[92:95], v[148:151], v[204:207], v[92:95]
	v_mfma_f32_16x16x32_bf16 v[88:91], v[164:167], v[204:207], v[88:91]
	v_mfma_f32_16x16x32_bf16 v[76:79], v[148:151], v[212:215], v[76:79]
	v_mfma_f32_16x16x32_bf16 v[72:75], v[164:167], v[212:215], v[72:75]
	s_setprio 0
	s_setprio 1
	v_mfma_f32_16x16x32_bf16 v[116:119], v[168:171], v[184:187], v[116:119]
	v_mfma_f32_16x16x32_bf16 v[112:115], v[176:179], v[184:187], v[112:115]
	v_mfma_f32_16x16x32_bf16 v[100:103], v[168:171], v[192:195], v[100:103]
	v_mfma_f32_16x16x32_bf16 v[96:99], v[176:179], v[192:195], v[96:99]
	v_mfma_f32_16x16x32_bf16 v[84:87], v[168:171], v[200:203], v[84:87]
	v_mfma_f32_16x16x32_bf16 v[80:83], v[176:179], v[200:203], v[80:83]
	v_mfma_f32_16x16x32_bf16 v[68:71], v[168:171], v[208:211], v[68:71]
	v_mfma_f32_16x16x32_bf16 v[64:67], v[176:179], v[208:211], v[64:67]
	v_mfma_f32_16x16x32_bf16 v[116:119], v[172:175], v[188:191], v[116:119]
	v_mfma_f32_16x16x32_bf16 v[112:115], v[180:183], v[188:191], v[112:115]
	v_mfma_f32_16x16x32_bf16 v[100:103], v[172:175], v[196:199], v[100:103]
	v_mfma_f32_16x16x32_bf16 v[96:99], v[180:183], v[196:199], v[96:99]
	s_barrier
	v_mfma_f32_16x16x32_bf16 v[84:87], v[172:175], v[204:207], v[84:87]
	v_mfma_f32_16x16x32_bf16 v[80:83], v[180:183], v[204:207], v[80:83]
	v_mfma_f32_16x16x32_bf16 v[68:71], v[172:175], v[212:215], v[68:71]
	v_mfma_f32_16x16x32_bf16 v[64:67], v[180:183], v[212:215], v[64:67]
	s_setprio 0
	s_add_i32 s65, s54, s45
	v_lshl_add_u64 v[216:217], s[36:37], 0, v[130:131]
	s_mov_b32 m0, s65
	ds_read_b128 v[184:187], v157 offset:16384
	ds_read_b128 v[188:191], v157 offset:17408
	ds_read_b128 v[192:195], v157 offset:18432
	ds_read_b128 v[196:199], v157 offset:19456
	ds_read_b128 v[200:203], v157 offset:20480
	ds_read_b128 v[204:207], v157 offset:21504
	ds_read_b128 v[208:211], v157 offset:22528
	ds_read_b128 v[212:215], v157 offset:23552
	global_load_lds_dwordx4 v[216:217], off
	s_add_i32 m0, s65, 0x2000
	s_add_u32 s66, s36, 0x80000
	v_lshl_add_u64 v[218:219], s[36:37], 0, v[134:135]
	s_addc_u32 s67, s37, 0
	s_add_i32 s65, s55, s45
	global_load_lds_dwordx4 v[218:219], off
	v_lshl_add_u64 v[220:221], s[66:67], 0, v[130:131]
	s_mov_b32 m0, s65
	v_lshl_add_u64 v[222:223], s[38:39], 0, v[132:133]
	global_load_lds_dwordx4 v[220:221], off
	v_lshl_add_u64 v[220:221], s[66:67], 0, v[134:135]
	s_add_i32 m0, s65, 0x2000
	s_nop 0
	global_load_lds_dwordx4 v[220:221], off
	v_lshl_add_u64 v[220:221], s[38:39], 0, v[128:129]
	s_mov_b32 m0, s46
	s_nop 0
	global_load_lds_dwordx4 v[220:221], off
	s_mov_b32 m0, s47
	s_nop 0
	global_load_lds_dwordx4 v[222:223], off
	s_waitcnt vmcnt(8)
	s_waitcnt lgkmcnt(0)
	s_barrier
	s_setprio 1
	s_waitcnt lgkmcnt(0)
	v_mfma_f32_16x16x32_bf16 v[60:63], v[144:147], v[184:187], v[60:63]
	v_mfma_f32_16x16x32_bf16 v[56:59], v[160:163], v[184:187], v[56:59]
	v_mfma_f32_16x16x32_bf16 v[44:47], v[144:147], v[192:195], v[44:47]
	v_mfma_f32_16x16x32_bf16 v[40:43], v[160:163], v[192:195], v[40:43]
	v_mfma_f32_16x16x32_bf16 v[28:31], v[144:147], v[200:203], v[28:31]
	v_mfma_f32_16x16x32_bf16 v[24:27], v[160:163], v[200:203], v[24:27]
	v_mfma_f32_16x16x32_bf16 v[12:15], v[144:147], v[208:211], v[12:15]
	v_mfma_f32_16x16x32_bf16 v[8:11], v[160:163], v[208:211], v[8:11]
	v_mfma_f32_16x16x32_bf16 v[60:63], v[148:151], v[188:191], v[60:63]
	v_mfma_f32_16x16x32_bf16 v[56:59], v[164:167], v[188:191], v[56:59]
	v_mfma_f32_16x16x32_bf16 v[44:47], v[148:151], v[196:199], v[44:47]
	v_mfma_f32_16x16x32_bf16 v[40:43], v[164:167], v[196:199], v[40:43]
	v_mfma_f32_16x16x32_bf16 v[28:31], v[148:151], v[204:207], v[28:31]
	v_mfma_f32_16x16x32_bf16 v[24:27], v[164:167], v[204:207], v[24:27]
	v_mfma_f32_16x16x32_bf16 v[12:15], v[148:151], v[212:215], v[12:15]
	v_mfma_f32_16x16x32_bf16 v[8:11], v[164:167], v[212:215], v[8:11]
	s_setprio 0
	s_setprio 1
	v_mfma_f32_16x16x32_bf16 v[52:55], v[168:171], v[184:187], v[52:55]
	v_mfma_f32_16x16x32_bf16 v[48:51], v[176:179], v[184:187], v[48:51]
	v_mfma_f32_16x16x32_bf16 v[36:39], v[168:171], v[192:195], v[36:39]
	v_mfma_f32_16x16x32_bf16 v[32:35], v[176:179], v[192:195], v[32:35]
	v_mfma_f32_16x16x32_bf16 v[20:23], v[168:171], v[200:203], v[20:23]
	v_mfma_f32_16x16x32_bf16 v[16:19], v[176:179], v[200:203], v[16:19]
	v_mfma_f32_16x16x32_bf16 v[4:7], v[168:171], v[208:211], v[4:7]
	v_mfma_f32_16x16x32_bf16 v[0:3], v[176:179], v[208:211], v[0:3]
	v_mfma_f32_16x16x32_bf16 v[52:55], v[172:175], v[188:191], v[52:55]
	v_mfma_f32_16x16x32_bf16 v[48:51], v[180:183], v[188:191], v[48:51]
	v_mfma_f32_16x16x32_bf16 v[36:39], v[172:175], v[196:199], v[36:39]
	v_mfma_f32_16x16x32_bf16 v[32:35], v[180:183], v[196:199], v[32:35]
	s_barrier
	v_mfma_f32_16x16x32_bf16 v[20:23], v[172:175], v[204:207], v[20:23]
	v_mfma_f32_16x16x32_bf16 v[16:19], v[180:183], v[204:207], v[16:19]
	v_mfma_f32_16x16x32_bf16 v[4:7], v[172:175], v[212:215], v[4:7]
	v_mfma_f32_16x16x32_bf16 v[0:3], v[180:183], v[212:215], v[0:3]
	s_setprio 0
	s_add_i32 s65, 0, 0x18000
	s_add_i32 s66, 0, 0x1c000
	v_add_u32_e32 v164, s65, v153
	v_add_u32_e32 v180, s66, v153
	ds_read_b128 v[144:147], v164
	ds_read_b128 v[148:151], v164 offset:1024
	ds_read_b128 v[160:163], v164 offset:2048
	ds_read_b128 v[164:167], v164 offset:3072
	ds_read_b128 v[168:171], v180
	ds_read_b128 v[172:175], v180 offset:1024
	ds_read_b128 v[176:179], v180 offset:2048
	ds_read_b128 v[180:183], v180 offset:3072
	s_add_u32 s38, s38, 0x80000
	s_addc_u32 s39, s39, 0
	s_mov_b32 m0, s48
	v_lshl_add_u64 v[224:225], s[38:39], 0, v[128:129]
	ds_read_b128 v[184:187], v157 offset:32768
	ds_read_b128 v[188:191], v157 offset:33792
	ds_read_b128 v[192:195], v157 offset:34816
	ds_read_b128 v[196:199], v157 offset:35840
	ds_read_b128 v[200:203], v157 offset:36864
	ds_read_b128 v[204:207], v157 offset:37888
	ds_read_b128 v[208:211], v157 offset:38912
	ds_read_b128 v[212:215], v157 offset:39936
	global_load_lds_dwordx4 v[224:225], off
	v_lshl_add_u64 v[224:225], s[38:39], 0, v[132:133]
	s_mov_b32 m0, s49
	s_nop 0
	global_load_lds_dwordx4 v[224:225], off
	s_waitcnt vmcnt(8)
	s_waitcnt lgkmcnt(0)
	s_barrier
	s_setprio 1
	s_waitcnt lgkmcnt(0)
	v_mfma_f32_16x16x32_bf16 v[124:127], v[144:147], v[184:187], v[124:127]
	v_mfma_f32_16x16x32_bf16 v[120:123], v[160:163], v[184:187], v[120:123]
	v_mfma_f32_16x16x32_bf16 v[108:111], v[144:147], v[192:195], v[108:111]
	v_mfma_f32_16x16x32_bf16 v[104:107], v[160:163], v[192:195], v[104:107]
	v_mfma_f32_16x16x32_bf16 v[92:95], v[144:147], v[200:203], v[92:95]
	v_mfma_f32_16x16x32_bf16 v[88:91], v[160:163], v[200:203], v[88:91]
	v_mfma_f32_16x16x32_bf16 v[76:79], v[144:147], v[208:211], v[76:79]
	v_mfma_f32_16x16x32_bf16 v[72:75], v[160:163], v[208:211], v[72:75]
	v_mfma_f32_16x16x32_bf16 v[124:127], v[148:151], v[188:191], v[124:127]
	v_mfma_f32_16x16x32_bf16 v[120:123], v[164:167], v[188:191], v[120:123]
	v_mfma_f32_16x16x32_bf16 v[108:111], v[148:151], v[196:199], v[108:111]
	v_mfma_f32_16x16x32_bf16 v[104:107], v[164:167], v[196:199], v[104:107]
	v_mfma_f32_16x16x32_bf16 v[92:95], v[148:151], v[204:207], v[92:95]
	v_mfma_f32_16x16x32_bf16 v[88:91], v[164:167], v[204:207], v[88:91]
	v_mfma_f32_16x16x32_bf16 v[76:79], v[148:151], v[212:215], v[76:79]
	v_mfma_f32_16x16x32_bf16 v[72:75], v[164:167], v[212:215], v[72:75]
	s_setprio 0
	s_setprio 1
	v_mfma_f32_16x16x32_bf16 v[116:119], v[168:171], v[184:187], v[116:119]
	v_mfma_f32_16x16x32_bf16 v[112:115], v[176:179], v[184:187], v[112:115]
	v_mfma_f32_16x16x32_bf16 v[100:103], v[168:171], v[192:195], v[100:103]
	v_mfma_f32_16x16x32_bf16 v[96:99], v[176:179], v[192:195], v[96:99]
	v_mfma_f32_16x16x32_bf16 v[84:87], v[168:171], v[200:203], v[84:87]
	v_mfma_f32_16x16x32_bf16 v[80:83], v[176:179], v[200:203], v[80:83]
	v_mfma_f32_16x16x32_bf16 v[68:71], v[168:171], v[208:211], v[68:71]
	v_mfma_f32_16x16x32_bf16 v[64:67], v[176:179], v[208:211], v[64:67]
	v_mfma_f32_16x16x32_bf16 v[116:119], v[172:175], v[188:191], v[116:119]
	v_mfma_f32_16x16x32_bf16 v[112:115], v[180:183], v[188:191], v[112:115]
	v_mfma_f32_16x16x32_bf16 v[100:103], v[172:175], v[196:199], v[100:103]
	v_mfma_f32_16x16x32_bf16 v[96:99], v[180:183], v[196:199], v[96:99]
	s_barrier
	v_mfma_f32_16x16x32_bf16 v[84:87], v[172:175], v[204:207], v[84:87]
	v_mfma_f32_16x16x32_bf16 v[80:83], v[180:183], v[204:207], v[80:83]
	v_mfma_f32_16x16x32_bf16 v[68:71], v[172:175], v[212:215], v[68:71]
	v_mfma_f32_16x16x32_bf16 v[64:67], v[180:183], v[212:215], v[64:67]
	s_setprio 0
	s_add_i32 s38, s65, s45
	v_lshl_add_u64 v[216:217], v[216:217], 0, s[10:11]
	s_mov_b32 m0, s38
	ds_read_b128 v[184:187], v157 offset:49152
	ds_read_b128 v[188:191], v157 offset:50176
	ds_read_b128 v[192:195], v157 offset:51200
	ds_read_b128 v[196:199], v157 offset:52224
	ds_read_b128 v[200:203], v157 offset:53248
	ds_read_b128 v[204:207], v157 offset:54272
	ds_read_b128 v[208:211], v157 offset:55296
	ds_read_b128 v[212:215], v157 offset:56320
	global_load_lds_dwordx4 v[216:217], off
	s_add_i32 m0, s38, 0x2000
	s_add_u32 s36, s36, 0x80080
	v_lshl_add_u64 v[216:217], v[218:219], 0, s[10:11]
	s_addc_u32 s37, s37, 0
	s_add_i32 s38, s66, s45
	global_load_lds_dwordx4 v[216:217], off
	v_lshl_add_u64 v[216:217], s[36:37], 0, v[130:131]
	s_mov_b32 m0, s38
	s_nop 0
	global_load_lds_dwordx4 v[216:217], off
	v_lshl_add_u64 v[216:217], s[36:37], 0, v[134:135]
	s_add_i32 m0, s38, 0x2000
	s_nop 0
	global_load_lds_dwordx4 v[216:217], off
	v_lshl_add_u64 v[216:217], v[220:221], 0, s[10:11]
	s_mov_b32 m0, s51
	s_nop 0
	global_load_lds_dwordx4 v[216:217], off
	v_lshl_add_u64 v[216:217], v[222:223], 0, s[10:11]
	s_mov_b32 m0, s52
	s_nop 0
	global_load_lds_dwordx4 v[216:217], off
	s_waitcnt vmcnt(8)
	s_waitcnt lgkmcnt(0)
	s_barrier
	s_setprio 1
	s_waitcnt lgkmcnt(0)
	v_mfma_f32_16x16x32_bf16 v[60:63], v[144:147], v[184:187], v[60:63]
	v_mfma_f32_16x16x32_bf16 v[56:59], v[160:163], v[184:187], v[56:59]
	v_mfma_f32_16x16x32_bf16 v[44:47], v[144:147], v[192:195], v[44:47]
	v_mfma_f32_16x16x32_bf16 v[40:43], v[160:163], v[192:195], v[40:43]
	v_mfma_f32_16x16x32_bf16 v[28:31], v[144:147], v[200:203], v[28:31]
	v_mfma_f32_16x16x32_bf16 v[24:27], v[160:163], v[200:203], v[24:27]
	v_mfma_f32_16x16x32_bf16 v[12:15], v[144:147], v[208:211], v[12:15]
	v_mfma_f32_16x16x32_bf16 v[8:11], v[160:163], v[208:211], v[8:11]
	v_mfma_f32_16x16x32_bf16 v[60:63], v[148:151], v[188:191], v[60:63]
	v_mfma_f32_16x16x32_bf16 v[56:59], v[164:167], v[188:191], v[56:59]
	v_mfma_f32_16x16x32_bf16 v[44:47], v[148:151], v[196:199], v[44:47]
	v_mfma_f32_16x16x32_bf16 v[40:43], v[164:167], v[196:199], v[40:43]
	v_mfma_f32_16x16x32_bf16 v[28:31], v[148:151], v[204:207], v[28:31]
	v_mfma_f32_16x16x32_bf16 v[24:27], v[164:167], v[204:207], v[24:27]
	v_mfma_f32_16x16x32_bf16 v[12:15], v[148:151], v[212:215], v[12:15]
	v_mfma_f32_16x16x32_bf16 v[8:11], v[164:167], v[212:215], v[8:11]
	s_setprio 0
	s_setprio 1
	v_mfma_f32_16x16x32_bf16 v[52:55], v[168:171], v[184:187], v[52:55]
	v_mfma_f32_16x16x32_bf16 v[48:51], v[176:179], v[184:187], v[48:51]
	v_mfma_f32_16x16x32_bf16 v[36:39], v[168:171], v[192:195], v[36:39]
	v_mfma_f32_16x16x32_bf16 v[32:35], v[176:179], v[192:195], v[32:35]
	v_mfma_f32_16x16x32_bf16 v[20:23], v[168:171], v[200:203], v[20:23]
	v_mfma_f32_16x16x32_bf16 v[16:19], v[176:179], v[200:203], v[16:19]
	v_mfma_f32_16x16x32_bf16 v[4:7], v[168:171], v[208:211], v[4:7]
	v_mfma_f32_16x16x32_bf16 v[0:3], v[176:179], v[208:211], v[0:3]
	v_mfma_f32_16x16x32_bf16 v[52:55], v[172:175], v[188:191], v[52:55]
	v_mfma_f32_16x16x32_bf16 v[48:51], v[180:183], v[188:191], v[48:51]
	v_mfma_f32_16x16x32_bf16 v[36:39], v[172:175], v[196:199], v[36:39]
	v_mfma_f32_16x16x32_bf16 v[32:35], v[180:183], v[196:199], v[32:35]
	s_barrier
	v_mfma_f32_16x16x32_bf16 v[20:23], v[172:175], v[204:207], v[20:23]
	v_mfma_f32_16x16x32_bf16 v[16:19], v[180:183], v[204:207], v[16:19]
	v_mfma_f32_16x16x32_bf16 v[4:7], v[172:175], v[212:215], v[4:7]
	v_mfma_f32_16x16x32_bf16 v[0:3], v[180:183], v[212:215], v[0:3]
	s_setprio 0
	s_add_i32 s64, s64, 2
	s_add_u32 s34, s34, 0x100
	s_addc_u32 s35, s35, 0
	s_add_u32 s62, s62, 0x100
	s_addc_u32 s63, s63, 0
	s_cmp_gt_u32 s64, 29
	s_cbranch_scc0 .LBB0_1426
	s_and_b64 vcc, exec, s[12:13]
	s_cbranch_vccz .LBB0_1429
	s_barrier

.LBB0_1505:
	ds_read_b128 v[140:143], v149
	ds_read_b128 v[152:155], v149 offset:1024
	ds_read_b128 v[156:159], v149 offset:2048
	ds_read_b128 v[160:163], v149 offset:3072
	ds_read_b128 v[164:167], v150
	ds_read_b128 v[168:171], v150 offset:1024
	ds_read_b128 v[172:175], v150 offset:2048
	ds_read_b128 v[176:179], v150 offset:3072
	s_add_u32 s34, s30, 0xffe00080
	s_addc_u32 s35, s31, -1
	s_cmpk_eq_i32 s57, 0x7c
	s_cselect_b32 s37, s19, s35
	s_cselect_b32 s36, s21, s34
	s_cselect_b32 s35, s23, s56
	s_cselect_b32 s34, s54, s55
	v_lshl_add_u64 v[144:145], s[30:31], 0, v[132:133]
	s_add_i32 m0, s29, 0xc000
	ds_read_b128 v[180:183], v151
	ds_read_b128 v[184:187], v151 offset:1024
	ds_read_b128 v[188:191], v151 offset:2048
	ds_read_b128 v[192:195], v151 offset:3072
	ds_read_b128 v[196:199], v151 offset:4096
	ds_read_b128 v[200:203], v151 offset:5120
	ds_read_b128 v[204:207], v151 offset:6144
	ds_read_b128 v[208:211], v151 offset:7168
	global_load_lds_dwordx4 v[144:145], off
	v_lshl_add_u64 v[144:145], s[30:31], 0, v[134:135]
	s_add_i32 m0, s29, 0xe000
	s_nop 0
	global_load_lds_dwordx4 v[144:145], off
	s_waitcnt vmcnt(8)
	s_waitcnt lgkmcnt(0)
	s_barrier
	s_setprio 1
	s_waitcnt lgkmcnt(0)
	v_mfma_f32_16x16x32_bf16 v[124:127], v[140:143], v[180:183], v[124:127]
	v_mfma_f32_16x16x32_bf16 v[120:123], v[156:159], v[180:183], v[120:123]
	v_mfma_f32_16x16x32_bf16 v[112:115], v[140:143], v[188:191], v[112:115]
	v_mfma_f32_16x16x32_bf16 v[104:107], v[156:159], v[188:191], v[104:107]
	v_mfma_f32_16x16x32_bf16 v[96:99], v[140:143], v[196:199], v[96:99]
	v_mfma_f32_16x16x32_bf16 v[88:91], v[156:159], v[196:199], v[88:91]
	v_mfma_f32_16x16x32_bf16 v[80:83], v[140:143], v[204:207], v[80:83]
	v_mfma_f32_16x16x32_bf16 v[72:75], v[156:159], v[204:207], v[72:75]
	v_mfma_f32_16x16x32_bf16 v[124:127], v[152:155], v[184:187], v[124:127]
	v_mfma_f32_16x16x32_bf16 v[120:123], v[160:163], v[184:187], v[120:123]
	v_mfma_f32_16x16x32_bf16 v[112:115], v[152:155], v[192:195], v[112:115]
	v_mfma_f32_16x16x32_bf16 v[104:107], v[160:163], v[192:195], v[104:107]
	v_mfma_f32_16x16x32_bf16 v[96:99], v[152:155], v[200:203], v[96:99]
	v_mfma_f32_16x16x32_bf16 v[88:91], v[160:163], v[200:203], v[88:91]
	v_mfma_f32_16x16x32_bf16 v[80:83], v[152:155], v[208:211], v[80:83]
	v_mfma_f32_16x16x32_bf16 v[72:75], v[160:163], v[208:211], v[72:75]
	s_setprio 0
	s_setprio 1
	v_mfma_f32_16x16x32_bf16 v[116:119], v[164:167], v[180:183], v[116:119]
	v_mfma_f32_16x16x32_bf16 v[108:111], v[172:175], v[180:183], v[108:111]
	v_mfma_f32_16x16x32_bf16 v[100:103], v[164:167], v[188:191], v[100:103]
	v_mfma_f32_16x16x32_bf16 v[92:95], v[172:175], v[188:191], v[92:95]
	v_mfma_f32_16x16x32_bf16 v[84:87], v[164:167], v[196:199], v[84:87]
	v_mfma_f32_16x16x32_bf16 v[76:79], v[172:175], v[196:199], v[76:79]
	v_mfma_f32_16x16x32_bf16 v[68:71], v[164:167], v[204:207], v[68:71]
	v_mfma_f32_16x16x32_bf16 v[64:67], v[172:175], v[204:207], v[64:67]
	v_mfma_f32_16x16x32_bf16 v[116:119], v[168:171], v[184:187], v[116:119]
	v_mfma_f32_16x16x32_bf16 v[108:111], v[176:179], v[184:187], v[108:111]
	v_mfma_f32_16x16x32_bf16 v[100:103], v[168:171], v[192:195], v[100:103]
	v_mfma_f32_16x16x32_bf16 v[92:95], v[176:179], v[192:195], v[92:95]
	s_barrier
	v_mfma_f32_16x16x32_bf16 v[84:87], v[168:171], v[200:203], v[84:87]
	v_mfma_f32_16x16x32_bf16 v[76:79], v[176:179], v[200:203], v[76:79]
	v_mfma_f32_16x16x32_bf16 v[68:71], v[168:171], v[208:211], v[68:71]
	v_mfma_f32_16x16x32_bf16 v[64:67], v[176:179], v[208:211], v[64:67]
	s_setprio 0
	s_add_i32 s58, s51, s43
	v_lshl_add_u64 v[144:145], s[34:35], 0, v[128:129]
	s_mov_b32 m0, s58
	ds_read_b128 v[180:183], v151 offset:16384
	ds_read_b128 v[184:187], v151 offset:17408
	ds_read_b128 v[188:191], v151 offset:18432
	ds_read_b128 v[192:195], v151 offset:19456
	ds_read_b128 v[196:199], v151 offset:20480
	ds_read_b128 v[200:203], v151 offset:21504
	ds_read_b128 v[204:207], v151 offset:22528
	ds_read_b128 v[208:211], v151 offset:23552
	global_load_lds_dwordx4 v[144:145], off
	s_add_i32 m0, s58, 0x2000
	s_add_u32 s58, s34, 0x200000
	v_lshl_add_u64 v[212:213], s[34:35], 0, v[130:131]
	s_addc_u32 s59, s35, 0
	s_add_i32 s60, s52, s43
	global_load_lds_dwordx4 v[212:213], off
	v_lshl_add_u64 v[214:215], s[58:59], 0, v[128:129]
	s_mov_b32 m0, s60
	v_lshl_add_u64 v[216:217], s[36:37], 0, v[130:131]
	global_load_lds_dwordx4 v[214:215], off
	v_lshl_add_u64 v[214:215], s[58:59], 0, v[130:131]
	s_add_i32 m0, s60, 0x2000
	s_nop 0
	global_load_lds_dwordx4 v[214:215], off
	v_lshl_add_u64 v[214:215], s[36:37], 0, v[128:129]
	s_mov_b32 m0, s29
	s_nop 0
	global_load_lds_dwordx4 v[214:215], off
	s_mov_b32 m0, s44
	s_nop 0
	global_load_lds_dwordx4 v[216:217], off
	s_waitcnt vmcnt(8)
	s_waitcnt lgkmcnt(0)
	s_barrier
	s_setprio 1
	s_waitcnt lgkmcnt(0)
	v_mfma_f32_16x16x32_bf16 v[60:63], v[140:143], v[180:183], v[60:63]
	v_mfma_f32_16x16x32_bf16 v[56:59], v[156:159], v[180:183], v[56:59]
	v_mfma_f32_16x16x32_bf16 v[48:51], v[140:143], v[188:191], v[48:51]
	v_mfma_f32_16x16x32_bf16 v[40:43], v[156:159], v[188:191], v[40:43]
	v_mfma_f32_16x16x32_bf16 v[32:35], v[140:143], v[196:199], v[32:35]
	v_mfma_f32_16x16x32_bf16 v[24:27], v[156:159], v[196:199], v[24:27]
	v_mfma_f32_16x16x32_bf16 v[16:19], v[140:143], v[204:207], v[16:19]
	v_mfma_f32_16x16x32_bf16 v[8:11], v[156:159], v[204:207], v[8:11]
	v_mfma_f32_16x16x32_bf16 v[60:63], v[152:155], v[184:187], v[60:63]
	v_mfma_f32_16x16x32_bf16 v[56:59], v[160:163], v[184:187], v[56:59]
	v_mfma_f32_16x16x32_bf16 v[48:51], v[152:155], v[192:195], v[48:51]
	v_mfma_f32_16x16x32_bf16 v[40:43], v[160:163], v[192:195], v[40:43]
	v_mfma_f32_16x16x32_bf16 v[32:35], v[152:155], v[200:203], v[32:35]
	v_mfma_f32_16x16x32_bf16 v[24:27], v[160:163], v[200:203], v[24:27]
	v_mfma_f32_16x16x32_bf16 v[16:19], v[152:155], v[208:211], v[16:19]
	v_mfma_f32_16x16x32_bf16 v[8:11], v[160:163], v[208:211], v[8:11]
	s_setprio 0
	s_setprio 1
	v_mfma_f32_16x16x32_bf16 v[52:55], v[164:167], v[180:183], v[52:55]
	v_mfma_f32_16x16x32_bf16 v[44:47], v[172:175], v[180:183], v[44:47]
	v_mfma_f32_16x16x32_bf16 v[36:39], v[164:167], v[188:191], v[36:39]
	v_mfma_f32_16x16x32_bf16 v[28:31], v[172:175], v[188:191], v[28:31]
	v_mfma_f32_16x16x32_bf16 v[20:23], v[164:167], v[196:199], v[20:23]
	v_mfma_f32_16x16x32_bf16 v[12:15], v[172:175], v[196:199], v[12:15]
	v_mfma_f32_16x16x32_bf16 v[4:7], v[164:167], v[204:207], v[4:7]
	v_mfma_f32_16x16x32_bf16 v[0:3], v[172:175], v[204:207], v[0:3]
	v_mfma_f32_16x16x32_bf16 v[52:55], v[168:171], v[184:187], v[52:55]
	v_mfma_f32_16x16x32_bf16 v[44:47], v[176:179], v[184:187], v[44:47]
	v_mfma_f32_16x16x32_bf16 v[36:39], v[168:171], v[192:195], v[36:39]
	v_mfma_f32_16x16x32_bf16 v[28:31], v[176:179], v[192:195], v[28:31]
	s_barrier
	v_mfma_f32_16x16x32_bf16 v[20:23], v[168:171], v[200:203], v[20:23]
	v_mfma_f32_16x16x32_bf16 v[12:15], v[176:179], v[200:203], v[12:15]
	v_mfma_f32_16x16x32_bf16 v[4:7], v[168:171], v[208:211], v[4:7]
	v_mfma_f32_16x16x32_bf16 v[0:3], v[176:179], v[208:211], v[0:3]
	s_setprio 0
	s_add_i32 s58, 0, 0x18000
	s_add_i32 s59, 0, 0x1c000
	v_add_u32_e32 v160, s58, v147
	v_add_u32_e32 v176, s59, v147
	ds_read_b128 v[140:143], v160
	ds_read_b128 v[152:155], v160 offset:1024
	ds_read_b128 v[156:159], v160 offset:2048
	ds_read_b128 v[160:163], v160 offset:3072
	ds_read_b128 v[164:167], v176
	ds_read_b128 v[168:171], v176 offset:1024
	ds_read_b128 v[172:175], v176 offset:2048
	ds_read_b128 v[176:179], v176 offset:3072
	s_add_u32 s36, s36, 0x200000
	s_addc_u32 s37, s37, 0
	s_mov_b32 m0, s45
	v_lshl_add_u64 v[218:219], s[36:37], 0, v[128:129]
	ds_read_b128 v[180:183], v151 offset:32768
	ds_read_b128 v[184:187], v151 offset:33792
	ds_read_b128 v[188:191], v151 offset:34816
	ds_read_b128 v[192:195], v151 offset:35840
	ds_read_b128 v[196:199], v151 offset:36864
	ds_read_b128 v[200:203], v151 offset:37888
	ds_read_b128 v[204:207], v151 offset:38912
	ds_read_b128 v[208:211], v151 offset:39936
	global_load_lds_dwordx4 v[218:219], off
	v_lshl_add_u64 v[218:219], s[36:37], 0, v[130:131]
	s_mov_b32 m0, s46
	s_nop 0
	global_load_lds_dwordx4 v[218:219], off
	s_waitcnt vmcnt(8)
	s_waitcnt lgkmcnt(0)
	s_barrier
	s_setprio 1
	s_waitcnt lgkmcnt(0)
	v_mfma_f32_16x16x32_bf16 v[124:127], v[140:143], v[180:183], v[124:127]
	v_mfma_f32_16x16x32_bf16 v[120:123], v[156:159], v[180:183], v[120:123]
	v_mfma_f32_16x16x32_bf16 v[112:115], v[140:143], v[188:191], v[112:115]
	v_mfma_f32_16x16x32_bf16 v[104:107], v[156:159], v[188:191], v[104:107]
	v_mfma_f32_16x16x32_bf16 v[96:99], v[140:143], v[196:199], v[96:99]
	v_mfma_f32_16x16x32_bf16 v[88:91], v[156:159], v[196:199], v[88:91]
	v_mfma_f32_16x16x32_bf16 v[80:83], v[140:143], v[204:207], v[80:83]
	v_mfma_f32_16x16x32_bf16 v[72:75], v[156:159], v[204:207], v[72:75]
	v_mfma_f32_16x16x32_bf16 v[124:127], v[152:155], v[184:187], v[124:127]
	v_mfma_f32_16x16x32_bf16 v[120:123], v[160:163], v[184:187], v[120:123]
	v_mfma_f32_16x16x32_bf16 v[112:115], v[152:155], v[192:195], v[112:115]
	v_mfma_f32_16x16x32_bf16 v[104:107], v[160:163], v[192:195], v[104:107]
	v_mfma_f32_16x16x32_bf16 v[96:99], v[152:155], v[200:203], v[96:99]
	v_mfma_f32_16x16x32_bf16 v[88:91], v[160:163], v[200:203], v[88:91]
	v_mfma_f32_16x16x32_bf16 v[80:83], v[152:155], v[208:211], v[80:83]
	v_mfma_f32_16x16x32_bf16 v[72:75], v[160:163], v[208:211], v[72:75]
	s_setprio 0
	s_setprio 1
	v_mfma_f32_16x16x32_bf16 v[116:119], v[164:167], v[180:183], v[116:119]
	v_mfma_f32_16x16x32_bf16 v[108:111], v[172:175], v[180:183], v[108:111]
	v_mfma_f32_16x16x32_bf16 v[100:103], v[164:167], v[188:191], v[100:103]
	v_mfma_f32_16x16x32_bf16 v[92:95], v[172:175], v[188:191], v[92:95]
	v_mfma_f32_16x16x32_bf16 v[84:87], v[164:167], v[196:199], v[84:87]
	v_mfma_f32_16x16x32_bf16 v[76:79], v[172:175], v[196:199], v[76:79]
	v_mfma_f32_16x16x32_bf16 v[68:71], v[164:167], v[204:207], v[68:71]
	v_mfma_f32_16x16x32_bf16 v[64:67], v[172:175], v[204:207], v[64:67]
	v_mfma_f32_16x16x32_bf16 v[116:119], v[168:171], v[184:187], v[116:119]
	v_mfma_f32_16x16x32_bf16 v[108:111], v[176:179], v[184:187], v[108:111]
	v_mfma_f32_16x16x32_bf16 v[100:103], v[168:171], v[192:195], v[100:103]
	v_mfma_f32_16x16x32_bf16 v[92:95], v[176:179], v[192:195], v[92:95]
	s_barrier
	v_mfma_f32_16x16x32_bf16 v[84:87], v[168:171], v[200:203], v[84:87]
	v_mfma_f32_16x16x32_bf16 v[76:79], v[176:179], v[200:203], v[76:79]
	v_mfma_f32_16x16x32_bf16 v[68:71], v[168:171], v[208:211], v[68:71]
	v_mfma_f32_16x16x32_bf16 v[64:67], v[176:179], v[208:211], v[64:67]
	s_setprio 0
	s_add_i32 s36, s58, s43
	v_lshl_add_u64 v[144:145], v[144:145], 0, s[6:7]
	s_mov_b32 m0, s36
	ds_read_b128 v[180:183], v151 offset:49152
	ds_read_b128 v[184:187], v151 offset:50176
	ds_read_b128 v[188:191], v151 offset:51200
	ds_read_b128 v[192:195], v151 offset:52224
	ds_read_b128 v[196:199], v151 offset:53248
	ds_read_b128 v[200:203], v151 offset:54272
	ds_read_b128 v[204:207], v151 offset:55296
	ds_read_b128 v[208:211], v151 offset:56320
	global_load_lds_dwordx4 v[144:145], off
	s_add_i32 m0, s36, 0x2000
	s_add_u32 s34, s34, 0x200080
	v_lshl_add_u64 v[144:145], v[212:213], 0, s[6:7]
	s_addc_u32 s35, s35, 0
	s_add_i32 s36, s59, s43
	global_load_lds_dwordx4 v[144:145], off
	v_lshl_add_u64 v[144:145], s[34:35], 0, v[128:129]
	s_mov_b32 m0, s36
	s_nop 0
	global_load_lds_dwordx4 v[144:145], off
	v_lshl_add_u64 v[144:145], s[34:35], 0, v[130:131]
	s_add_i32 m0, s36, 0x2000
	s_nop 0
	global_load_lds_dwordx4 v[144:145], off
	v_lshl_add_u64 v[144:145], v[214:215], 0, s[6:7]
	s_mov_b32 m0, s48
	s_nop 0
	global_load_lds_dwordx4 v[144:145], off
	v_lshl_add_u64 v[144:145], v[216:217], 0, s[6:7]
	s_mov_b32 m0, s49
	s_nop 0
	global_load_lds_dwordx4 v[144:145], off
	s_waitcnt vmcnt(8)
	s_waitcnt lgkmcnt(0)
	s_barrier
	s_setprio 1
	s_waitcnt lgkmcnt(0)
	v_mfma_f32_16x16x32_bf16 v[60:63], v[140:143], v[180:183], v[60:63]
	v_mfma_f32_16x16x32_bf16 v[56:59], v[156:159], v[180:183], v[56:59]
	v_mfma_f32_16x16x32_bf16 v[48:51], v[140:143], v[188:191], v[48:51]
	v_mfma_f32_16x16x32_bf16 v[40:43], v[156:159], v[188:191], v[40:43]
	v_mfma_f32_16x16x32_bf16 v[32:35], v[140:143], v[196:199], v[32:35]
	v_mfma_f32_16x16x32_bf16 v[24:27], v[156:159], v[196:199], v[24:27]
	v_mfma_f32_16x16x32_bf16 v[16:19], v[140:143], v[204:207], v[16:19]
	v_mfma_f32_16x16x32_bf16 v[8:11], v[156:159], v[204:207], v[8:11]
	v_mfma_f32_16x16x32_bf16 v[60:63], v[152:155], v[184:187], v[60:63]
	v_mfma_f32_16x16x32_bf16 v[56:59], v[160:163], v[184:187], v[56:59]
	v_mfma_f32_16x16x32_bf16 v[48:51], v[152:155], v[192:195], v[48:51]
	v_mfma_f32_16x16x32_bf16 v[40:43], v[160:163], v[192:195], v[40:43]
	v_mfma_f32_16x16x32_bf16 v[32:35], v[152:155], v[200:203], v[32:35]
	v_mfma_f32_16x16x32_bf16 v[24:27], v[160:163], v[200:203], v[24:27]
	v_mfma_f32_16x16x32_bf16 v[16:19], v[152:155], v[208:211], v[16:19]
	v_mfma_f32_16x16x32_bf16 v[8:11], v[160:163], v[208:211], v[8:11]
	s_setprio 0
	s_setprio 1
	v_mfma_f32_16x16x32_bf16 v[52:55], v[164:167], v[180:183], v[52:55]
	v_mfma_f32_16x16x32_bf16 v[44:47], v[172:175], v[180:183], v[44:47]
	v_mfma_f32_16x16x32_bf16 v[36:39], v[164:167], v[188:191], v[36:39]
	v_mfma_f32_16x16x32_bf16 v[28:31], v[172:175], v[188:191], v[28:31]
	v_mfma_f32_16x16x32_bf16 v[20:23], v[164:167], v[196:199], v[20:23]
	v_mfma_f32_16x16x32_bf16 v[12:15], v[172:175], v[196:199], v[12:15]
	v_mfma_f32_16x16x32_bf16 v[4:7], v[164:167], v[204:207], v[4:7]
	v_mfma_f32_16x16x32_bf16 v[0:3], v[172:175], v[204:207], v[0:3]
	v_mfma_f32_16x16x32_bf16 v[52:55], v[168:171], v[184:187], v[52:55]
	v_mfma_f32_16x16x32_bf16 v[44:47], v[176:179], v[184:187], v[44:47]
	v_mfma_f32_16x16x32_bf16 v[36:39], v[168:171], v[192:195], v[36:39]
	v_mfma_f32_16x16x32_bf16 v[28:31], v[176:179], v[192:195], v[28:31]
	s_barrier
	v_mfma_f32_16x16x32_bf16 v[20:23], v[168:171], v[200:203], v[20:23]
	v_mfma_f32_16x16x32_bf16 v[12:15], v[176:179], v[200:203], v[12:15]
	v_mfma_f32_16x16x32_bf16 v[4:7], v[168:171], v[208:211], v[4:7]
	v_mfma_f32_16x16x32_bf16 v[0:3], v[176:179], v[208:211], v[0:3]
	s_setprio 0
	s_add_i32 s57, s57, 2
	s_add_u32 s30, s30, 0x100
	s_addc_u32 s31, s31, 0
	s_add_u32 s55, s55, 0x100
	s_addc_u32 s56, s56, 0
	s_cmpk_gt_u32 s57, 0x7d
	s_cbranch_scc0 .LBB0_1505
	s_and_b64 vcc, exec, s[8:9]
	s_cbranch_vccz .LBB0_1508
	s_barrier
